# K-loop LDS-DMA: 10 more address pairs to scalar-base form (offset+0x80 in a 32-bit VGPR), total 57 of 80 loads without 64-bit VALU adds; setprio flips deleted; previous edits
# baseline (speedup 1.0000x reference)
;     __device__ __forceinline__ void prefetch(const Unit& u, int wr, int wc, int lane) const { lnfold_prefetch(vl, stats, gW, bW, u, wr, wc, lane); }
;     __device__ __forceinline__ void prefetch(const Unit& u, int wr, int wc, int lane) const { lnfold_prefetch(vl, stats, gW, bW, u, wr, wc, lane); }
; #define PG8_STAGE(bufoff, gbase, voff) do { _Pragma("unroll") for (int _i = 0; _i < 2; ++_i) \
;         __builtin_amdgcn_global_load_lds((const unsigned*)((const char*)(gbase) + (voff)[_i]), (LAS unsigned*)(lds + (bufoff) + ldsw + _i * 8192), 16, 0, 0); } while (0)
; #define PG8_LDA(dst, b, h) do { _Pragma("unroll") for (int m = 0; m < 4; ++m) _Pragma("unroll") for (int k = 0; k < 2; ++k) dst[m][k] = *(const LAS f16x8*)(lds + PG8_SA(b, h) + aoff + m * 2048 + k * 1024); } while (0)
; #define PG8_LDB(dst, b, h) do { _Pragma("unroll") for (int n = 0; n < 2; ++n) _Pragma("unroll") for (int k = 0; k < 2; ++k) dst[n][k] = *(const LAS f16x8*)(lds + PG8_SB(b, h) + boff + n * 2048 + k * 1024); } while (0)
; #define PG8_WAIT_L(n) asm volatile("s_waitcnt lgkmcnt(" #n ")" ::: "memory")
; #define PG8_BAR __builtin_amdgcn_s_barrier()
; template <class Epi>
; __device__ __forceinline__ void gemm_phase(LAS unsigned char* lds, const Gemm g0, const StaticOrder& S, const Epi& E) {
;     ...
;         const char* nA = has_next ? (const char*)g.A + (size_t)nxt.pm * tstep : cA; const char* nB = has_next ? (const char*)g.Bt + (size_t)nxt.pn * tstep : cB;
;         for (int t = 0; t < nt; t += 2) {
;             const bool last = (t == nt - 2);
;             if (Epi::PREF && last) E.prefetch(cur, wr, wc, lane);
;             const char* a1 = cA + (size_t)(t + 1) * kstep;
;             const char* a2 = last ? nA : cA + (size_t)(t + 2) * kstep; const char* b2 = last ? nB : cB + (size_t)(t + 2) * kstep;
;             const char* a3 = a2 + kstep; const char* b3 = b2 + kstep;
;             PG8_LDB(B0, 0, 0); PG8_SCHED; PG8_LDA(At, 0, 0); PG8_STAGE(PG8_SA(1, 1), a1 + hstep, voffA);
;             PG8_WAIT_L(8); PG8_BAR; PG8_WAIT_L(0); PG8_MMA(0, 0, At, B0); PG8_BAR; PG8_SCHED;
;             PG8_LDB(B1, 0, 1); PG8_STAGE(PG8_SB(0, 0), b2, voffB);
;             PG8_BAR; PG8_WAIT_L(0); PG8_MMA(0, 1, At, B1); PG8_BAR;
;             PG8_LDA(At, 0, 1); PG8_STAGE(PG8_SA(0, 0), a2, voffA);
;             PG8_BAR; PG8_WAIT_L(0); PG8_MMA(1, 0, At, B0); PG8_BAR; PG8_SCHED;
.LBB0_198:
	s_add_u32 s52, s0, 0xfff80080
	s_addc_u32 s53, s1, -1
	s_and_b64 s[22:23], s[50:51], exec
	s_cselect_b32 s53, s75, s53
	s_cselect_b32 s52, s80, s52
	s_add_i32 s84, 0, 0x10000
	v_add_u32_e32 v148, s84, v214
	ds_read_b128 v[136:139], v148
	ds_read_b128 v[140:143], v148 offset:1024
	ds_read_b128 v[144:147], v148 offset:2048
	ds_read_b128 v[148:151], v148 offset:3072
	s_and_b64 s[22:23], s[50:51], exec
	s_cselect_b32 s51, s81, s25
	s_cselect_b32 s50, s82, s24
	s_add_i32 m0, s28, 0xc000
	ds_read_b128 v[152:155], v222
	ds_read_b128 v[156:159], v222 offset:1024
	ds_read_b128 v[186:189], v222 offset:2048
	ds_read_b128 v[190:193], v222 offset:3072
	ds_read_b128 v[194:197], v222 offset:4096
	ds_read_b128 v[198:201], v222 offset:5120
	ds_read_b128 v[202:205], v222 offset:6144
	ds_read_b128 v[206:209], v222 offset:7168
	global_load_lds_dwordx4 v184, s[0:1]
	s_add_i32 m0, s28, 0xe000
	s_nop 0
	global_load_lds_dwordx4 v182, s[0:1]
	s_waitcnt lgkmcnt(8)
	s_barrier
	s_waitcnt lgkmcnt(0)
	s_waitcnt lgkmcnt(0)
	v_mfma_f32_16x16x32_f16 v[126:129], v[136:139], v[152:155], v[126:129]
	v_mfma_f32_16x16x32_f16 v[122:125], v[144:147], v[152:155], v[122:125]
	v_mfma_f32_16x16x32_f16 v[118:121], v[136:139], v[186:189], v[118:121]
	v_mfma_f32_16x16x32_f16 v[110:113], v[144:147], v[186:189], v[110:113]
	v_mfma_f32_16x16x32_f16 v[102:105], v[136:139], v[194:197], v[102:105]
	v_mfma_f32_16x16x32_f16 v[98:101], v[144:147], v[194:197], v[98:101]
	v_mfma_f32_16x16x32_f16 v[86:89], v[136:139], v[202:205], v[86:89]
	v_mfma_f32_16x16x32_f16 v[82:85], v[144:147], v[202:205], v[82:85]
	v_mfma_f32_16x16x32_f16 v[126:129], v[140:143], v[156:159], v[126:129]
	v_mfma_f32_16x16x32_f16 v[122:125], v[148:151], v[156:159], v[122:125]
	v_mfma_f32_16x16x32_f16 v[118:121], v[140:143], v[190:193], v[118:121]
	v_mfma_f32_16x16x32_f16 v[110:113], v[148:151], v[190:193], v[110:113]
	v_mfma_f32_16x16x32_f16 v[102:105], v[140:143], v[198:201], v[102:105]
	v_mfma_f32_16x16x32_f16 v[98:101], v[148:151], v[198:201], v[98:101]
	v_mfma_f32_16x16x32_f16 v[86:89], v[140:143], v[206:209], v[86:89]
	v_mfma_f32_16x16x32_f16 v[82:85], v[148:151], v[206:209], v[82:85]
	s_barrier
	s_add_i32 s85, 0, 0x14000
	v_add_u32_e32 v160, s85, v214
	s_add_i32 s22, s84, s19
	ds_read_b128 v[210:213], v160
	ds_read_b128 v[234:237], v160 offset:1024
	ds_read_b128 v[238:241], v160 offset:2048
	ds_read_b128 v[242:245], v160 offset:3072
	v_add_u32_e32 v160, 0x80, v178
	s_mov_b32 m0, s22
	v_add_u32_e32 v162, 0x80, v174
	global_load_lds_dwordx4 v178, s[50:51]
	s_add_i32 m0, s22, 0x2000
	s_nop 0
	global_load_lds_dwordx4 v174, s[50:51]
	s_barrier
	s_waitcnt lgkmcnt(0)
	s_waitcnt lgkmcnt(0)
	v_mfma_f32_16x16x32_f16 v[114:117], v[210:213], v[152:155], v[114:117]
	v_mfma_f32_16x16x32_f16 v[106:109], v[238:241], v[152:155], v[106:109]
	v_mfma_f32_16x16x32_f16 v[94:97], v[210:213], v[186:189], v[94:97]
	v_mfma_f32_16x16x32_f16 v[90:93], v[238:241], v[186:189], v[90:93]
	v_mfma_f32_16x16x32_f16 v[78:81], v[210:213], v[194:197], v[78:81]
	v_mfma_f32_16x16x32_f16 v[74:77], v[238:241], v[194:197], v[74:77]
	v_mfma_f32_16x16x32_f16 v[70:73], v[210:213], v[202:205], v[70:73]
	v_mfma_f32_16x16x32_f16 v[66:69], v[238:241], v[202:205], v[66:69]
	v_mfma_f32_16x16x32_f16 v[114:117], v[234:237], v[156:159], v[114:117]
	v_mfma_f32_16x16x32_f16 v[106:109], v[242:245], v[156:159], v[106:109]
	v_mfma_f32_16x16x32_f16 v[94:97], v[234:237], v[190:193], v[94:97]
	v_mfma_f32_16x16x32_f16 v[90:93], v[242:245], v[190:193], v[90:93]
	v_mfma_f32_16x16x32_f16 v[78:81], v[234:237], v[198:201], v[78:81]
	v_mfma_f32_16x16x32_f16 v[74:77], v[242:245], v[198:201], v[74:77]
	v_mfma_f32_16x16x32_f16 v[70:73], v[234:237], v[206:209], v[70:73]
	v_mfma_f32_16x16x32_f16 v[66:69], v[242:245], v[206:209], v[66:69]
	s_mov_b32 m0, s28
	v_lshl_add_u64 v[164:165], s[52:53], 0, v[180:181]
	s_barrier
	ds_read_b128 v[152:155], v222 offset:16384
	ds_read_b128 v[156:159], v222 offset:17408
	ds_read_b128 v[186:189], v222 offset:18432
	ds_read_b128 v[190:193], v222 offset:19456
	ds_read_b128 v[194:197], v222 offset:20480
	ds_read_b128 v[198:201], v222 offset:21504
	ds_read_b128 v[202:205], v222 offset:22528
	ds_read_b128 v[206:209], v222 offset:23552
	global_load_lds_dwordx4 v[164:165], off
	v_lshl_add_u64 v[170:171], s[52:53], 0, v[176:177]
	s_mov_b32 m0, s29
	s_nop 0
	global_load_lds_dwordx4 v[170:171], off
	s_barrier
	s_waitcnt lgkmcnt(0)
	s_waitcnt lgkmcnt(0)
	v_mfma_f32_16x16x32_f16 v[62:65], v[136:139], v[152:155], v[62:65]
	v_mfma_f32_16x16x32_f16 v[58:61], v[144:147], v[152:155], v[58:61]
	v_mfma_f32_16x16x32_f16 v[54:57], v[136:139], v[186:189], v[54:57]
	v_mfma_f32_16x16x32_f16 v[50:53], v[144:147], v[186:189], v[50:53]
	v_mfma_f32_16x16x32_f16 v[38:41], v[136:139], v[194:197], v[38:41]
	v_mfma_f32_16x16x32_f16 v[30:33], v[144:147], v[194:197], v[30:33]
	v_mfma_f32_16x16x32_f16 v[22:25], v[136:139], v[202:205], v[22:25]
	v_mfma_f32_16x16x32_f16 v[18:21], v[144:147], v[202:205], v[18:21]
	v_mfma_f32_16x16x32_f16 v[62:65], v[140:143], v[156:159], v[62:65]
	v_mfma_f32_16x16x32_f16 v[58:61], v[148:151], v[156:159], v[58:61]
	v_mfma_f32_16x16x32_f16 v[54:57], v[140:143], v[190:193], v[54:57]
	v_mfma_f32_16x16x32_f16 v[50:53], v[148:151], v[190:193], v[50:53]
	v_mfma_f32_16x16x32_f16 v[38:41], v[140:143], v[198:201], v[38:41]
	v_mfma_f32_16x16x32_f16 v[30:33], v[148:151], v[198:201], v[30:33]
	v_mfma_f32_16x16x32_f16 v[22:25], v[140:143], v[206:209], v[22:25]
	v_mfma_f32_16x16x32_f16 v[18:21], v[148:151], v[206:209], v[18:21]
	s_barrier
; #define PG8_STAGE(bufoff, gbase, voff) do { _Pragma("unroll") for (int _i = 0; _i < 2; ++_i) \
;         __builtin_amdgcn_global_load_lds((const unsigned*)((const char*)(gbase) + (voff)[_i]), (LAS unsigned*)(lds + (bufoff) + ldsw + _i * 8192), 16, 0, 0); } while (0)
; #define PG8_LDA(dst, b, h) do { _Pragma("unroll") for (int m = 0; m < 4; ++m) _Pragma("unroll") for (int k = 0; k < 2; ++k) dst[m][k] = *(const LAS f16x8*)(lds + PG8_SA(b, h) + aoff + m * 2048 + k * 1024); } while (0)
; #define PG8_LDB(dst, b, h) do { _Pragma("unroll") for (int n = 0; n < 2; ++n) _Pragma("unroll") for (int k = 0; k < 2; ++k) dst[n][k] = *(const LAS f16x8*)(lds + PG8_SB(b, h) + boff + n * 2048 + k * 1024); } while (0)
; #define PG8_MMA(ai, bj, At, Bt) do { __builtin_amdgcn_s_setprio(1); _Pragma("unroll") for (int m = 0; m < 4; ++m) _Pragma("unroll") for (int n = 0; n < 2; ++n) _Pragma("unroll") for (int k = 0; k < 2; ++k) \
;         acc[ai][bj][m][n] = __builtin_amdgcn_mfma_f32_16x16x32_f16(Bt[n][k], At[m][k], acc[ai][bj][m][n], 0, 0, 0); __builtin_amdgcn_s_setprio(0); } while (0)
; #define PG8_WAIT_V(n) asm volatile("s_waitcnt vmcnt(" #n ")" ::: "memory")
; #define PG8_WAIT_L(n) asm volatile("s_waitcnt lgkmcnt(" #n ")" ::: "memory")
; #define PG8_BAR __builtin_amdgcn_s_barrier()
; #define PG8_SCHED __builtin_amdgcn_sched_barrier(0)
; template <class Epi>
; __device__ __forceinline__ void gemm_phase(LAS unsigned char* lds, const Gemm g0, const StaticOrder& S, const Epi& E) {
;     ...
;             PG8_STAGE(PG8_SB(0, 1), b2 + hstep, voffB);
;             PG8_WAIT_V(6); PG8_BAR; PG8_MMA(1, 1, At, B1); PG8_BAR;
;             PG8_LDB(B0, 1, 0); PG8_SCHED; PG8_LDA(At, 1, 0); PG8_STAGE(PG8_SA(0, 1), a2 + hstep, voffA);
;             PG8_WAIT_L(8); PG8_BAR; PG8_WAIT_L(0); PG8_MMA(0, 0, At, B0); PG8_BAR; PG8_SCHED;
;             PG8_LDB(B1, 1, 1); PG8_STAGE(PG8_SB(1, 0), b3, voffB);
	s_add_u32 s22, s50, 0x80000
	s_addc_u32 s23, s51, 0
	s_add_i32 s84, s85, s19
	s_mov_b32 m0, s84
	s_nop 0
	global_load_lds_dwordx4 v178, s[22:23]
	s_add_i32 m0, s84, 0x2000
	s_nop 0
	global_load_lds_dwordx4 v174, s[22:23]
	s_waitcnt vmcnt(6)
	s_barrier
	v_mfma_f32_16x16x32_f16 v[46:49], v[210:213], v[152:155], v[46:49]
	v_mfma_f32_16x16x32_f16 v[42:45], v[238:241], v[152:155], v[42:45]
	v_mfma_f32_16x16x32_f16 v[34:37], v[210:213], v[186:189], v[34:37]
	v_mfma_f32_16x16x32_f16 v[26:29], v[238:241], v[186:189], v[26:29]
	v_mfma_f32_16x16x32_f16 v[14:17], v[210:213], v[194:197], v[14:17]
	v_mfma_f32_16x16x32_f16 v[10:13], v[238:241], v[194:197], v[10:13]
	v_mfma_f32_16x16x32_f16 v[6:9], v[210:213], v[202:205], v[6:9]
	v_mfma_f32_16x16x32_f16 v[2:5], v[238:241], v[202:205], v[2:5]
	v_mfma_f32_16x16x32_f16 v[46:49], v[234:237], v[156:159], v[46:49]
	v_mfma_f32_16x16x32_f16 v[42:45], v[242:245], v[156:159], v[42:45]
	v_mfma_f32_16x16x32_f16 v[34:37], v[234:237], v[190:193], v[34:37]
	v_mfma_f32_16x16x32_f16 v[26:29], v[242:245], v[190:193], v[26:29]
	v_mfma_f32_16x16x32_f16 v[14:17], v[234:237], v[198:201], v[14:17]
	v_mfma_f32_16x16x32_f16 v[10:13], v[242:245], v[198:201], v[10:13]
	v_mfma_f32_16x16x32_f16 v[6:9], v[234:237], v[206:209], v[6:9]
	v_mfma_f32_16x16x32_f16 v[2:5], v[242:245], v[206:209], v[2:5]
	s_add_i32 s84, 0, 0x18000
	v_add_u32_e32 v148, s84, v214
	s_barrier
	ds_read_b128 v[136:139], v148
	ds_read_b128 v[140:143], v148 offset:1024
	ds_read_b128 v[144:147], v148 offset:2048
	ds_read_b128 v[148:151], v148 offset:3072
	s_add_u32 s22, s52, 0x80000
	s_addc_u32 s23, s53, 0
	s_mov_b32 m0, s31
	ds_read_b128 v[152:155], v222 offset:32768
	ds_read_b128 v[156:159], v222 offset:33792
	ds_read_b128 v[186:189], v222 offset:34816
	ds_read_b128 v[190:193], v222 offset:35840
	ds_read_b128 v[194:197], v222 offset:36864
	ds_read_b128 v[198:201], v222 offset:37888
	ds_read_b128 v[202:205], v222 offset:38912
	ds_read_b128 v[206:209], v222 offset:39936
	global_load_lds_dwordx4 v180, s[22:23]
	s_mov_b32 m0, s58
	s_nop 0
	global_load_lds_dwordx4 v176, s[22:23]
	s_waitcnt lgkmcnt(8)
	s_barrier
	s_waitcnt lgkmcnt(0)
	s_waitcnt lgkmcnt(0)
	v_mfma_f32_16x16x32_f16 v[126:129], v[136:139], v[152:155], v[126:129]
	v_mfma_f32_16x16x32_f16 v[122:125], v[144:147], v[152:155], v[122:125]
	v_mfma_f32_16x16x32_f16 v[118:121], v[136:139], v[186:189], v[118:121]
	v_mfma_f32_16x16x32_f16 v[110:113], v[144:147], v[186:189], v[110:113]
	v_mfma_f32_16x16x32_f16 v[102:105], v[136:139], v[194:197], v[102:105]
	v_mfma_f32_16x16x32_f16 v[98:101], v[144:147], v[194:197], v[98:101]
	v_mfma_f32_16x16x32_f16 v[86:89], v[136:139], v[202:205], v[86:89]
	v_mfma_f32_16x16x32_f16 v[82:85], v[144:147], v[202:205], v[82:85]
	v_mfma_f32_16x16x32_f16 v[126:129], v[140:143], v[156:159], v[126:129]
	v_mfma_f32_16x16x32_f16 v[122:125], v[148:151], v[156:159], v[122:125]
	v_mfma_f32_16x16x32_f16 v[118:121], v[140:143], v[190:193], v[118:121]
	v_mfma_f32_16x16x32_f16 v[110:113], v[148:151], v[190:193], v[110:113]
	v_mfma_f32_16x16x32_f16 v[102:105], v[140:143], v[198:201], v[102:105]
	v_mfma_f32_16x16x32_f16 v[98:101], v[148:151], v[198:201], v[98:101]
	v_mfma_f32_16x16x32_f16 v[86:89], v[140:143], v[206:209], v[86:89]
	v_mfma_f32_16x16x32_f16 v[82:85], v[148:151], v[206:209], v[82:85]
	s_barrier
	s_add_i32 s52, 0, 0x1c000
	s_add_i32 s22, s84, s19
	v_add_u32_e32 v172, s52, v214
	s_mov_b32 m0, s22
	ds_read_b128 v[210:213], v172
	ds_read_b128 v[234:237], v172 offset:1024
	ds_read_b128 v[238:241], v172 offset:2048
	ds_read_b128 v[242:245], v172 offset:3072
	global_load_lds_dwordx4 v160, s[50:51]
	s_add_i32 m0, s22, 0x2000
	s_nop 0
	global_load_lds_dwordx4 v162, s[50:51]
	s_barrier
; #define PG8_STAGE(bufoff, gbase, voff) do { _Pragma("unroll") for (int _i = 0; _i < 2; ++_i) \
;         __builtin_amdgcn_global_load_lds((const unsigned*)((const char*)(gbase) + (voff)[_i]), (LAS unsigned*)(lds + (bufoff) + ldsw + _i * 8192), 16, 0, 0); } while (0)
; #define PG8_LDA(dst, b, h) do { _Pragma("unroll") for (int m = 0; m < 4; ++m) _Pragma("unroll") for (int k = 0; k < 2; ++k) dst[m][k] = *(const LAS f16x8*)(lds + PG8_SA(b, h) + aoff + m * 2048 + k * 1024); } while (0)
; #define PG8_MMA(ai, bj, At, Bt) do { __builtin_amdgcn_s_setprio(1); _Pragma("unroll") for (int m = 0; m < 4; ++m) _Pragma("unroll") for (int n = 0; n < 2; ++n) _Pragma("unroll") for (int k = 0; k < 2; ++k) \
;         acc[ai][bj][m][n] = __builtin_amdgcn_mfma_f32_16x16x32_f16(Bt[n][k], At[m][k], acc[ai][bj][m][n], 0, 0, 0); __builtin_amdgcn_s_setprio(0); } while (0)
; #define PG8_WAIT_V(n) asm volatile("s_waitcnt vmcnt(" #n ")" ::: "memory")
; #define PG8_WAIT_L(n) asm volatile("s_waitcnt lgkmcnt(" #n ")" ::: "memory")
; #define PG8_BAR __builtin_amdgcn_s_barrier()
; #define PG8_SCHED __builtin_amdgcn_sched_barrier(0)
; template <class Epi>
; __device__ __forceinline__ void gemm_phase(LAS unsigned char* lds, const Gemm g0, const StaticOrder& S, const Epi& E) {
;     ...
;             PG8_BAR; PG8_WAIT_L(0); PG8_MMA(0, 1, At, B1); PG8_BAR;
;             PG8_LDA(At, 1, 1); PG8_STAGE(PG8_SA(1, 0), a3, voffA);
;             PG8_BAR; PG8_WAIT_L(0); PG8_MMA(1, 0, At, B0); PG8_BAR; PG8_SCHED;
;             PG8_STAGE(PG8_SB(1, 1), b3 + hstep, voffB);
;             PG8_WAIT_V(6); PG8_BAR; PG8_MMA(1, 1, At, B1); PG8_BAR;
;         }
	s_waitcnt lgkmcnt(0)
	s_waitcnt lgkmcnt(0)
	v_mfma_f32_16x16x32_f16 v[114:117], v[210:213], v[152:155], v[114:117]
	v_mfma_f32_16x16x32_f16 v[106:109], v[238:241], v[152:155], v[106:109]
	v_mfma_f32_16x16x32_f16 v[94:97], v[210:213], v[186:189], v[94:97]
	v_mfma_f32_16x16x32_f16 v[90:93], v[238:241], v[186:189], v[90:93]
	v_mfma_f32_16x16x32_f16 v[78:81], v[210:213], v[194:197], v[78:81]
	v_mfma_f32_16x16x32_f16 v[74:77], v[238:241], v[194:197], v[74:77]
	v_mfma_f32_16x16x32_f16 v[70:73], v[210:213], v[202:205], v[70:73]
	v_mfma_f32_16x16x32_f16 v[66:69], v[238:241], v[202:205], v[66:69]
	v_mfma_f32_16x16x32_f16 v[114:117], v[234:237], v[156:159], v[114:117]
	v_mfma_f32_16x16x32_f16 v[106:109], v[242:245], v[156:159], v[106:109]
	v_mfma_f32_16x16x32_f16 v[94:97], v[234:237], v[190:193], v[94:97]
	v_mfma_f32_16x16x32_f16 v[90:93], v[242:245], v[190:193], v[90:93]
	v_mfma_f32_16x16x32_f16 v[78:81], v[234:237], v[198:201], v[78:81]
	v_mfma_f32_16x16x32_f16 v[74:77], v[242:245], v[198:201], v[74:77]
	v_mfma_f32_16x16x32_f16 v[70:73], v[234:237], v[206:209], v[70:73]
	v_mfma_f32_16x16x32_f16 v[66:69], v[242:245], v[206:209], v[66:69]
	s_mov_b32 m0, s59
	v_lshl_add_u64 v[160:161], v[164:165], 0, s[64:65]
	s_barrier
	ds_read_b128 v[152:155], v222 offset:49152
	ds_read_b128 v[156:159], v222 offset:50176
	ds_read_b128 v[186:189], v222 offset:51200
	ds_read_b128 v[190:193], v222 offset:52224
	ds_read_b128 v[194:197], v222 offset:53248
	ds_read_b128 v[198:201], v222 offset:54272
	ds_read_b128 v[202:205], v222 offset:55296
	ds_read_b128 v[206:209], v222 offset:56320
	global_load_lds_dwordx4 v[160:161], off
	v_lshl_add_u64 v[160:161], v[170:171], 0, s[64:65]
	s_mov_b32 m0, s61
	s_nop 0
	global_load_lds_dwordx4 v[160:161], off
	s_barrier
	s_waitcnt lgkmcnt(0)
	s_waitcnt lgkmcnt(0)
	v_mfma_f32_16x16x32_f16 v[62:65], v[136:139], v[152:155], v[62:65]
	v_mfma_f32_16x16x32_f16 v[58:61], v[144:147], v[152:155], v[58:61]
	v_mfma_f32_16x16x32_f16 v[54:57], v[136:139], v[186:189], v[54:57]
	v_mfma_f32_16x16x32_f16 v[50:53], v[144:147], v[186:189], v[50:53]
	v_mfma_f32_16x16x32_f16 v[38:41], v[136:139], v[194:197], v[38:41]
	v_mfma_f32_16x16x32_f16 v[30:33], v[144:147], v[194:197], v[30:33]
	v_mfma_f32_16x16x32_f16 v[22:25], v[136:139], v[202:205], v[22:25]
	v_mfma_f32_16x16x32_f16 v[18:21], v[144:147], v[202:205], v[18:21]
	v_mfma_f32_16x16x32_f16 v[62:65], v[140:143], v[156:159], v[62:65]
	v_mfma_f32_16x16x32_f16 v[58:61], v[148:151], v[156:159], v[58:61]
	v_mfma_f32_16x16x32_f16 v[54:57], v[140:143], v[190:193], v[54:57]
	v_mfma_f32_16x16x32_f16 v[50:53], v[148:151], v[190:193], v[50:53]
	v_mfma_f32_16x16x32_f16 v[38:41], v[140:143], v[198:201], v[38:41]
	v_mfma_f32_16x16x32_f16 v[30:33], v[148:151], v[198:201], v[30:33]
	v_mfma_f32_16x16x32_f16 v[22:25], v[140:143], v[206:209], v[22:25]
	v_mfma_f32_16x16x32_f16 v[18:21], v[148:151], v[206:209], v[18:21]
	s_barrier
	s_add_u32 s22, s50, 0x80080
	s_addc_u32 s23, s51, 0
	s_add_i32 s50, s52, s19
	s_mov_b32 m0, s50
	s_nop 0
	global_load_lds_dwordx4 v178, s[22:23]
	v_lshl_add_u64 v[136:137], s[22:23], 0, v[174:175]
	s_add_i32 m0, s50, 0x2000
	s_nop 0
	global_load_lds_dwordx4 v[136:137], off
	s_waitcnt vmcnt(6)
	s_barrier
	v_mfma_f32_16x16x32_f16 v[46:49], v[210:213], v[152:155], v[46:49]
	v_mfma_f32_16x16x32_f16 v[42:45], v[238:241], v[152:155], v[42:45]
	v_mfma_f32_16x16x32_f16 v[34:37], v[210:213], v[186:189], v[34:37]
	v_mfma_f32_16x16x32_f16 v[26:29], v[238:241], v[186:189], v[26:29]
	v_mfma_f32_16x16x32_f16 v[14:17], v[210:213], v[194:197], v[14:17]
	v_mfma_f32_16x16x32_f16 v[10:13], v[238:241], v[194:197], v[10:13]
	v_mfma_f32_16x16x32_f16 v[6:9], v[210:213], v[202:205], v[6:9]
	v_mfma_f32_16x16x32_f16 v[2:5], v[238:241], v[202:205], v[2:5]
	v_mfma_f32_16x16x32_f16 v[46:49], v[234:237], v[156:159], v[46:49]
	v_mfma_f32_16x16x32_f16 v[42:45], v[242:245], v[156:159], v[42:45]
	v_mfma_f32_16x16x32_f16 v[34:37], v[234:237], v[190:193], v[34:37]
	v_mfma_f32_16x16x32_f16 v[26:29], v[242:245], v[190:193], v[26:29]
	v_mfma_f32_16x16x32_f16 v[14:17], v[234:237], v[198:201], v[14:17]
	v_mfma_f32_16x16x32_f16 v[10:13], v[242:245], v[198:201], v[10:13]
	v_mfma_f32_16x16x32_f16 v[6:9], v[234:237], v[206:209], v[6:9]
	v_mfma_f32_16x16x32_f16 v[2:5], v[242:245], v[206:209], v[2:5]
	s_add_i32 s83, s83, 2
	s_add_u32 s24, s24, 0x100
	s_addc_u32 s25, s25, 0
	s_add_u32 s0, s0, 0x100
	s_addc_u32 s1, s1, 0
	s_cmp_gt_u32 s83, 29
	s_barrier
	s_cbranch_scc1 .LBB0_201

;     __device__ __forceinline__ void prefetch(const Unit& u, int wr, int wc, int lane) const { lnfold_prefetch(vl, stats, gW, bW, u, wr, wc, lane); }
;     __device__ __forceinline__ void prefetch(const Unit& u, int wr, int wc, int lane) const { lnfold_prefetch(vl, stats, gW, bW, u, wr, wc, lane); }
; #define PG8_STAGE(bufoff, gbase, voff) do { _Pragma("unroll") for (int _i = 0; _i < 2; ++_i) \
;         __builtin_amdgcn_global_load_lds((const unsigned*)((const char*)(gbase) + (voff)[_i]), (LAS unsigned*)(lds + (bufoff) + ldsw + _i * 8192), 16, 0, 0); } while (0)
; #define PG8_LDA(dst, b, h) do { _Pragma("unroll") for (int m = 0; m < 4; ++m) _Pragma("unroll") for (int k = 0; k < 2; ++k) dst[m][k] = *(const LAS f16x8*)(lds + PG8_SA(b, h) + aoff + m * 2048 + k * 1024); } while (0)
; #define PG8_LDB(dst, b, h) do { _Pragma("unroll") for (int n = 0; n < 2; ++n) _Pragma("unroll") for (int k = 0; k < 2; ++k) dst[n][k] = *(const LAS f16x8*)(lds + PG8_SB(b, h) + boff + n * 2048 + k * 1024); } while (0)
; template <class Epi>
; __device__ __forceinline__ void gemm_phase(LAS unsigned char* lds, const Gemm g0, const StaticOrder& S, const Epi& E) {
;     ...
;         const char* nA = has_next ? (const char*)g.A + (size_t)nxt.pm * tstep : cA; const char* nB = has_next ? (const char*)g.Bt + (size_t)nxt.pn * tstep : cB;
;         for (int t = 0; t < nt; t += 2) {
;             const bool last = (t == nt - 2);
;             if (Epi::PREF && last) E.prefetch(cur, wr, wc, lane);
;             const char* a1 = cA + (size_t)(t + 1) * kstep;
;             const char* a2 = last ? nA : cA + (size_t)(t + 2) * kstep; const char* b2 = last ? nB : cB + (size_t)(t + 2) * kstep;
;             const char* a3 = a2 + kstep; const char* b3 = b2 + kstep;
;             PG8_LDB(B0, 0, 0); PG8_SCHED; PG8_LDA(At, 0, 0); PG8_STAGE(PG8_SA(1, 1), a1 + hstep, voffA);
;             PG8_WAIT_L(8); PG8_BAR; PG8_WAIT_L(0); PG8_MMA(0, 0, At, B0); PG8_BAR; PG8_SCHED;
;             PG8_LDB(B1, 0, 1); PG8_STAGE(PG8_SB(0, 0), b2, voffB);
;             PG8_BAR; PG8_WAIT_L(0); PG8_MMA(0, 1, At, B1); PG8_BAR;
;             PG8_LDA(At, 0, 1); PG8_STAGE(PG8_SA(0, 0), a2, voffA);
;             PG8_BAR; PG8_WAIT_L(0); PG8_MMA(1, 0, At, B0); PG8_BAR; PG8_SCHED;
;             PG8_STAGE(PG8_SB(0, 1), b2 + hstep, voffB);
;             PG8_WAIT_V(6); PG8_BAR; PG8_MMA(1, 1, At, B1); PG8_BAR;
.LBB0_302:
	s_add_u32 s22, s6, 0xfff80080
	s_addc_u32 s23, s7, -1
	s_add_i32 s59, 0, 0x10000
	v_add_u32_e32 v146, s59, v148
	ds_read_b128 v[142:145], v146
	ds_read_b128 v[152:155], v146 offset:1024
	ds_read_b128 v[156:159], v146 offset:2048
	ds_read_b128 v[174:177], v146 offset:3072
	s_cmp_eq_u32 s58, 28
	s_cselect_b32 s37, s15, s23
	s_cselect_b32 s36, s52, s22
	s_cselect_b32 s35, s13, s53
	s_cselect_b32 s34, s24, s25
	s_add_i32 m0, s28, 0xc000
	ds_read_b128 v[178:181], v150
	ds_read_b128 v[182:185], v150 offset:1024
	ds_read_b128 v[186:189], v150 offset:2048
	ds_read_b128 v[190:193], v150 offset:3072
	ds_read_b128 v[194:197], v150 offset:4096
	ds_read_b128 v[198:201], v150 offset:5120
	ds_read_b128 v[202:205], v150 offset:6144
	ds_read_b128 v[206:209], v150 offset:7168
	global_load_lds_dwordx4 v140, s[6:7]
	s_add_i32 m0, s28, 0xe000
	s_nop 0
	global_load_lds_dwordx4 v138, s[6:7]
	s_waitcnt lgkmcnt(8)
	s_barrier
	s_waitcnt lgkmcnt(0)
	s_waitcnt lgkmcnt(0)
	v_mfma_f32_16x16x32_f16 v[126:129], v[142:145], v[178:181], v[126:129]
	v_mfma_f32_16x16x32_f16 v[122:125], v[156:159], v[178:181], v[122:125]
	v_mfma_f32_16x16x32_f16 v[110:113], v[142:145], v[186:189], v[110:113]
	v_mfma_f32_16x16x32_f16 v[106:109], v[156:159], v[186:189], v[106:109]
	v_mfma_f32_16x16x32_f16 v[94:97], v[142:145], v[194:197], v[94:97]
	v_mfma_f32_16x16x32_f16 v[90:93], v[156:159], v[194:197], v[90:93]
	v_mfma_f32_16x16x32_f16 v[78:81], v[142:145], v[202:205], v[78:81]
	v_mfma_f32_16x16x32_f16 v[74:77], v[156:159], v[202:205], v[74:77]
	v_mfma_f32_16x16x32_f16 v[126:129], v[152:155], v[182:185], v[126:129]
	v_mfma_f32_16x16x32_f16 v[122:125], v[174:177], v[182:185], v[122:125]
	v_mfma_f32_16x16x32_f16 v[110:113], v[152:155], v[190:193], v[110:113]
	v_mfma_f32_16x16x32_f16 v[106:109], v[174:177], v[190:193], v[106:109]
	v_mfma_f32_16x16x32_f16 v[94:97], v[152:155], v[198:201], v[94:97]
	v_mfma_f32_16x16x32_f16 v[90:93], v[174:177], v[198:201], v[90:93]
	v_mfma_f32_16x16x32_f16 v[78:81], v[152:155], v[206:209], v[78:81]
	v_mfma_f32_16x16x32_f16 v[74:77], v[174:177], v[206:209], v[74:77]
	s_barrier
	s_add_i32 s61, 0, 0x14000
	v_add_u32_e32 v146, s61, v148
	s_add_i32 s22, s59, s19
	ds_read_b128 v[210:213], v146
	ds_read_b128 v[234:237], v146 offset:1024
	ds_read_b128 v[238:241], v146 offset:2048
	ds_read_b128 v[242:245], v146 offset:3072
	v_add_u32_e32 v146, 0x80, v134
	s_mov_b32 m0, s22
	v_add_u32_e32 v160, 0x80, v130
	global_load_lds_dwordx4 v134, s[34:35]
	s_add_i32 m0, s22, 0x2000
	s_nop 0
	global_load_lds_dwordx4 v130, s[34:35]
	s_barrier
	s_waitcnt lgkmcnt(0)
	s_waitcnt lgkmcnt(0)
	v_mfma_f32_16x16x32_f16 v[118:121], v[210:213], v[178:181], v[118:121]
	v_mfma_f32_16x16x32_f16 v[114:117], v[238:241], v[178:181], v[114:117]
	v_mfma_f32_16x16x32_f16 v[102:105], v[210:213], v[186:189], v[102:105]
	v_mfma_f32_16x16x32_f16 v[98:101], v[238:241], v[186:189], v[98:101]
	v_mfma_f32_16x16x32_f16 v[86:89], v[210:213], v[194:197], v[86:89]
	v_mfma_f32_16x16x32_f16 v[82:85], v[238:241], v[194:197], v[82:85]
	v_mfma_f32_16x16x32_f16 v[70:73], v[210:213], v[202:205], v[70:73]
	v_mfma_f32_16x16x32_f16 v[66:69], v[238:241], v[202:205], v[66:69]
	v_mfma_f32_16x16x32_f16 v[118:121], v[234:237], v[182:185], v[118:121]
	v_mfma_f32_16x16x32_f16 v[114:117], v[242:245], v[182:185], v[114:117]
	v_mfma_f32_16x16x32_f16 v[102:105], v[234:237], v[190:193], v[102:105]
	v_mfma_f32_16x16x32_f16 v[98:101], v[242:245], v[190:193], v[98:101]
	v_mfma_f32_16x16x32_f16 v[86:89], v[234:237], v[198:201], v[86:89]
	v_mfma_f32_16x16x32_f16 v[82:85], v[242:245], v[198:201], v[82:85]
	v_mfma_f32_16x16x32_f16 v[70:73], v[234:237], v[206:209], v[70:73]
	v_mfma_f32_16x16x32_f16 v[66:69], v[242:245], v[206:209], v[66:69]
	s_mov_b32 m0, s28
	v_lshl_add_u64 v[162:163], s[36:37], 0, v[136:137]
	s_barrier
	ds_read_b128 v[178:181], v150 offset:16384
	ds_read_b128 v[182:185], v150 offset:17408
	ds_read_b128 v[186:189], v150 offset:18432
	ds_read_b128 v[190:193], v150 offset:19456
	ds_read_b128 v[194:197], v150 offset:20480
	ds_read_b128 v[198:201], v150 offset:21504
	ds_read_b128 v[202:205], v150 offset:22528
	ds_read_b128 v[206:209], v150 offset:23552
	global_load_lds_dwordx4 v[162:163], off
	v_lshl_add_u64 v[164:165], s[36:37], 0, v[132:133]
	s_mov_b32 m0, s29
	s_nop 0
	global_load_lds_dwordx4 v[164:165], off
	s_barrier
	s_waitcnt lgkmcnt(0)
	s_waitcnt lgkmcnt(0)
	v_mfma_f32_16x16x32_f16 v[62:65], v[142:145], v[178:181], v[62:65]
	v_mfma_f32_16x16x32_f16 v[58:61], v[156:159], v[178:181], v[58:61]
	v_mfma_f32_16x16x32_f16 v[46:49], v[142:145], v[186:189], v[46:49]
	v_mfma_f32_16x16x32_f16 v[42:45], v[156:159], v[186:189], v[42:45]
	v_mfma_f32_16x16x32_f16 v[30:33], v[142:145], v[194:197], v[30:33]
	v_mfma_f32_16x16x32_f16 v[26:29], v[156:159], v[194:197], v[26:29]
	v_mfma_f32_16x16x32_f16 v[14:17], v[142:145], v[202:205], v[14:17]
	v_mfma_f32_16x16x32_f16 v[10:13], v[156:159], v[202:205], v[10:13]
	v_mfma_f32_16x16x32_f16 v[62:65], v[152:155], v[182:185], v[62:65]
	v_mfma_f32_16x16x32_f16 v[58:61], v[174:177], v[182:185], v[58:61]
	v_mfma_f32_16x16x32_f16 v[46:49], v[152:155], v[190:193], v[46:49]
	v_mfma_f32_16x16x32_f16 v[42:45], v[174:177], v[190:193], v[42:45]
	v_mfma_f32_16x16x32_f16 v[30:33], v[152:155], v[198:201], v[30:33]
	v_mfma_f32_16x16x32_f16 v[26:29], v[174:177], v[198:201], v[26:29]
	v_mfma_f32_16x16x32_f16 v[14:17], v[152:155], v[206:209], v[14:17]
	v_mfma_f32_16x16x32_f16 v[10:13], v[174:177], v[206:209], v[10:13]
	s_barrier
	s_add_u32 s22, s34, 0x80000
	s_addc_u32 s23, s35, 0
	s_add_i32 s59, s61, s19
	s_mov_b32 m0, s59
	s_nop 0
	global_load_lds_dwordx4 v134, s[22:23]
	s_add_i32 m0, s59, 0x2000
	s_nop 0
	global_load_lds_dwordx4 v130, s[22:23]
	s_waitcnt vmcnt(6)
	s_barrier
; #define PG8_STAGE(bufoff, gbase, voff) do { _Pragma("unroll") for (int _i = 0; _i < 2; ++_i) \
;         __builtin_amdgcn_global_load_lds((const unsigned*)((const char*)(gbase) + (voff)[_i]), (LAS unsigned*)(lds + (bufoff) + ldsw + _i * 8192), 16, 0, 0); } while (0)
; #define PG8_LDA(dst, b, h) do { _Pragma("unroll") for (int m = 0; m < 4; ++m) _Pragma("unroll") for (int k = 0; k < 2; ++k) dst[m][k] = *(const LAS f16x8*)(lds + PG8_SA(b, h) + aoff + m * 2048 + k * 1024); } while (0)
; #define PG8_LDB(dst, b, h) do { _Pragma("unroll") for (int n = 0; n < 2; ++n) _Pragma("unroll") for (int k = 0; k < 2; ++k) dst[n][k] = *(const LAS f16x8*)(lds + PG8_SB(b, h) + boff + n * 2048 + k * 1024); } while (0)
; #define PG8_MMA(ai, bj, At, Bt) do { __builtin_amdgcn_s_setprio(1); _Pragma("unroll") for (int m = 0; m < 4; ++m) _Pragma("unroll") for (int n = 0; n < 2; ++n) _Pragma("unroll") for (int k = 0; k < 2; ++k) \
;         acc[ai][bj][m][n] = __builtin_amdgcn_mfma_f32_16x16x32_f16(Bt[n][k], At[m][k], acc[ai][bj][m][n], 0, 0, 0); __builtin_amdgcn_s_setprio(0); } while (0)
; #define PG8_WAIT_V(n) asm volatile("s_waitcnt vmcnt(" #n ")" ::: "memory")
; #define PG8_WAIT_L(n) asm volatile("s_waitcnt lgkmcnt(" #n ")" ::: "memory")
; #define PG8_BAR __builtin_amdgcn_s_barrier()
; #define PG8_SCHED __builtin_amdgcn_sched_barrier(0)
; template <class Epi>
; __device__ __forceinline__ void gemm_phase(LAS unsigned char* lds, const Gemm g0, const StaticOrder& S, const Epi& E) {
;     ...
;             PG8_WAIT_V(6); PG8_BAR; PG8_MMA(1, 1, At, B1); PG8_BAR;
;             PG8_LDB(B0, 1, 0); PG8_SCHED; PG8_LDA(At, 1, 0); PG8_STAGE(PG8_SA(0, 1), a2 + hstep, voffA);
;             PG8_WAIT_L(8); PG8_BAR; PG8_WAIT_L(0); PG8_MMA(0, 0, At, B0); PG8_BAR; PG8_SCHED;
;             PG8_LDB(B1, 1, 1); PG8_STAGE(PG8_SB(1, 0), b3, voffB);
;             PG8_BAR; PG8_WAIT_L(0); PG8_MMA(0, 1, At, B1); PG8_BAR;
;             PG8_LDA(At, 1, 1); PG8_STAGE(PG8_SA(1, 0), a3, voffA);
	v_mfma_f32_16x16x32_f16 v[54:57], v[210:213], v[178:181], v[54:57]
	v_mfma_f32_16x16x32_f16 v[50:53], v[238:241], v[178:181], v[50:53]
	v_mfma_f32_16x16x32_f16 v[38:41], v[210:213], v[186:189], v[38:41]
	v_mfma_f32_16x16x32_f16 v[34:37], v[238:241], v[186:189], v[34:37]
	v_mfma_f32_16x16x32_f16 v[22:25], v[210:213], v[194:197], v[22:25]
	v_mfma_f32_16x16x32_f16 v[18:21], v[238:241], v[194:197], v[18:21]
	v_mfma_f32_16x16x32_f16 v[6:9], v[210:213], v[202:205], v[6:9]
	v_mfma_f32_16x16x32_f16 v[2:5], v[238:241], v[202:205], v[2:5]
	v_mfma_f32_16x16x32_f16 v[54:57], v[234:237], v[182:185], v[54:57]
	v_mfma_f32_16x16x32_f16 v[50:53], v[242:245], v[182:185], v[50:53]
	v_mfma_f32_16x16x32_f16 v[38:41], v[234:237], v[190:193], v[38:41]
	v_mfma_f32_16x16x32_f16 v[34:37], v[242:245], v[190:193], v[34:37]
	v_mfma_f32_16x16x32_f16 v[22:25], v[234:237], v[198:201], v[22:25]
	v_mfma_f32_16x16x32_f16 v[18:21], v[242:245], v[198:201], v[18:21]
	v_mfma_f32_16x16x32_f16 v[6:9], v[234:237], v[206:209], v[6:9]
	v_mfma_f32_16x16x32_f16 v[2:5], v[242:245], v[206:209], v[2:5]
	s_add_i32 s59, 0, 0x18000
	v_add_u32_e32 v151, s59, v148
	s_barrier
	ds_read_b128 v[142:145], v151
	ds_read_b128 v[152:155], v151 offset:1024
	ds_read_b128 v[156:159], v151 offset:2048
	ds_read_b128 v[174:177], v151 offset:3072
	s_add_u32 s22, s36, 0x80000
	s_addc_u32 s23, s37, 0
	s_mov_b32 m0, s31
	ds_read_b128 v[178:181], v150 offset:32768
	ds_read_b128 v[182:185], v150 offset:33792
	ds_read_b128 v[186:189], v150 offset:34816
	ds_read_b128 v[190:193], v150 offset:35840
	ds_read_b128 v[194:197], v150 offset:36864
	ds_read_b128 v[198:201], v150 offset:37888
	ds_read_b128 v[202:205], v150 offset:38912
	ds_read_b128 v[206:209], v150 offset:39936
	global_load_lds_dwordx4 v136, s[22:23]
	v_lshl_add_u64 v[170:171], s[22:23], 0, v[132:133]
	s_mov_b32 m0, s38
	s_nop 0
	global_load_lds_dwordx4 v[170:171], off
	s_waitcnt lgkmcnt(8)
	s_barrier
	s_waitcnt lgkmcnt(0)
	s_waitcnt lgkmcnt(0)
	v_mfma_f32_16x16x32_f16 v[126:129], v[142:145], v[178:181], v[126:129]
	v_mfma_f32_16x16x32_f16 v[122:125], v[156:159], v[178:181], v[122:125]
	v_mfma_f32_16x16x32_f16 v[110:113], v[142:145], v[186:189], v[110:113]
	v_mfma_f32_16x16x32_f16 v[106:109], v[156:159], v[186:189], v[106:109]
	v_mfma_f32_16x16x32_f16 v[94:97], v[142:145], v[194:197], v[94:97]
	v_mfma_f32_16x16x32_f16 v[90:93], v[156:159], v[194:197], v[90:93]
	v_mfma_f32_16x16x32_f16 v[78:81], v[142:145], v[202:205], v[78:81]
	v_mfma_f32_16x16x32_f16 v[74:77], v[156:159], v[202:205], v[74:77]
	v_mfma_f32_16x16x32_f16 v[126:129], v[152:155], v[182:185], v[126:129]
	v_mfma_f32_16x16x32_f16 v[122:125], v[174:177], v[182:185], v[122:125]
	v_mfma_f32_16x16x32_f16 v[110:113], v[152:155], v[190:193], v[110:113]
	v_mfma_f32_16x16x32_f16 v[106:109], v[174:177], v[190:193], v[106:109]
	v_mfma_f32_16x16x32_f16 v[94:97], v[152:155], v[198:201], v[94:97]
	v_mfma_f32_16x16x32_f16 v[90:93], v[174:177], v[198:201], v[90:93]
	v_mfma_f32_16x16x32_f16 v[78:81], v[152:155], v[206:209], v[78:81]
	v_mfma_f32_16x16x32_f16 v[74:77], v[174:177], v[206:209], v[74:77]
	s_barrier
	s_add_i32 s36, 0, 0x1c000
	s_add_i32 s22, s59, s19
	v_add_u32_e32 v151, s36, v148
	s_mov_b32 m0, s22
	ds_read_b128 v[210:213], v151
	ds_read_b128 v[234:237], v151 offset:1024
	ds_read_b128 v[238:241], v151 offset:2048
	ds_read_b128 v[242:245], v151 offset:3072
	global_load_lds_dwordx4 v146, s[34:35]
	s_add_i32 m0, s22, 0x2000
	s_nop 0
	global_load_lds_dwordx4 v160, s[34:35]
	s_barrier
	s_waitcnt lgkmcnt(0)
	s_waitcnt lgkmcnt(0)
	v_mfma_f32_16x16x32_f16 v[118:121], v[210:213], v[178:181], v[118:121]
	v_mfma_f32_16x16x32_f16 v[114:117], v[238:241], v[178:181], v[114:117]
	v_mfma_f32_16x16x32_f16 v[102:105], v[210:213], v[186:189], v[102:105]
	v_mfma_f32_16x16x32_f16 v[98:101], v[238:241], v[186:189], v[98:101]
	v_mfma_f32_16x16x32_f16 v[86:89], v[210:213], v[194:197], v[86:89]
	v_mfma_f32_16x16x32_f16 v[82:85], v[238:241], v[194:197], v[82:85]
	v_mfma_f32_16x16x32_f16 v[70:73], v[210:213], v[202:205], v[70:73]
	v_mfma_f32_16x16x32_f16 v[66:69], v[238:241], v[202:205], v[66:69]
	v_mfma_f32_16x16x32_f16 v[118:121], v[234:237], v[182:185], v[118:121]
	v_mfma_f32_16x16x32_f16 v[114:117], v[242:245], v[182:185], v[114:117]
	v_mfma_f32_16x16x32_f16 v[102:105], v[234:237], v[190:193], v[102:105]
	v_mfma_f32_16x16x32_f16 v[98:101], v[242:245], v[190:193], v[98:101]
	v_mfma_f32_16x16x32_f16 v[86:89], v[234:237], v[198:201], v[86:89]
	v_mfma_f32_16x16x32_f16 v[82:85], v[242:245], v[198:201], v[82:85]
	v_mfma_f32_16x16x32_f16 v[70:73], v[234:237], v[206:209], v[70:73]
	v_mfma_f32_16x16x32_f16 v[66:69], v[242:245], v[206:209], v[66:69]
	s_mov_b32 m0, s39
	v_lshl_add_u64 v[146:147], v[162:163], 0, s[64:65]
	s_barrier
	ds_read_b128 v[178:181], v150 offset:49152
	ds_read_b128 v[182:185], v150 offset:50176
	ds_read_b128 v[186:189], v150 offset:51200
	ds_read_b128 v[190:193], v150 offset:52224
	ds_read_b128 v[194:197], v150 offset:53248
	ds_read_b128 v[198:201], v150 offset:54272
	ds_read_b128 v[202:205], v150 offset:55296
	ds_read_b128 v[206:209], v150 offset:56320
	global_load_lds_dwordx4 v[146:147], off
	v_lshl_add_u64 v[146:147], v[164:165], 0, s[64:65]
	s_mov_b32 m0, s48
	s_nop 0
	global_load_lds_dwordx4 v[146:147], off
	s_barrier
; __device__ __forceinline__ float gelu_tanh(float x) { const float y = 1.5957691216057308f * (x + 0.044715f * x * x * x); return x * fast_rcp(1.0f + __expf(-y)); }
; #define PG8_STAGE(bufoff, gbase, voff) do { _Pragma("unroll") for (int _i = 0; _i < 2; ++_i) \
;         __builtin_amdgcn_global_load_lds((const unsigned*)((const char*)(gbase) + (voff)[_i]), (LAS unsigned*)(lds + (bufoff) + ldsw + _i * 8192), 16, 0, 0); } while (0)
; #define PG8_MMA(ai, bj, At, Bt) do { __builtin_amdgcn_s_setprio(1); _Pragma("unroll") for (int m = 0; m < 4; ++m) _Pragma("unroll") for (int n = 0; n < 2; ++n) _Pragma("unroll") for (int k = 0; k < 2; ++k) \
;         acc[ai][bj][m][n] = __builtin_amdgcn_mfma_f32_16x16x32_f16(Bt[n][k], At[m][k], acc[ai][bj][m][n], 0, 0, 0); __builtin_amdgcn_s_setprio(0); } while (0)
; #define PG8_WAIT_V(n) asm volatile("s_waitcnt vmcnt(" #n ")" ::: "memory")
; #define PG8_WAIT_L(n) asm volatile("s_waitcnt lgkmcnt(" #n ")" ::: "memory")
; #define PG8_BAR __builtin_amdgcn_s_barrier()
; #define PG8_SCHED __builtin_amdgcn_sched_barrier(0)
;     __device__ __forceinline__ void operator()(f32x4 (&acc)[2][2][4][2], const Unit& u, int wr, int wc, int fr, int fq) const {
;         const bool isy = u.pn < 8; h16* dst = isy ? ybr : xpre; const int colb = (isy ? u.pn : u.pn - 8) * BM + wc * 32 + 8 * fq;
;         const int row0 = u.pm * BM + wr * 64 + fr;
; #pragma unroll
;         for (int ai = 0; ai < 2; ++ai)
; #pragma unroll
;             for (int m = 0; m < 4; ++m) { h16* rowp = dst + (size_t)(row0 + ai * HALF + m * 16) * DM + colb;
; #pragma unroll
;                 for (int bj = 0; bj < 2; ++bj) { f32x4 v0 = acc[ai][bj][m][0], v1 = acc[ai][bj][m][1];
;                     if (isy) {
; #pragma unroll
;                         for (int j = 0; j < 4; ++j) { v0[j] = gelu_tanh(v0[j]); v1[j] = gelu_tanh(v1[j]); } }
; template <class Epi>
; __device__ __forceinline__ void gemm_phase(LAS unsigned char* lds, const Gemm g0, const StaticOrder& S, const Epi& E) {
;     ...
;             PG8_BAR; PG8_WAIT_L(0); PG8_MMA(1, 0, At, B0); PG8_BAR; PG8_SCHED;
;             PG8_STAGE(PG8_SB(1, 1), b3 + hstep, voffB);
;             PG8_WAIT_V(6); PG8_BAR; PG8_MMA(1, 1, At, B1); PG8_BAR;
;         }
	s_waitcnt lgkmcnt(0)
	s_waitcnt lgkmcnt(0)
	v_mfma_f32_16x16x32_f16 v[62:65], v[142:145], v[178:181], v[62:65]
	v_mfma_f32_16x16x32_f16 v[58:61], v[156:159], v[178:181], v[58:61]
	v_mfma_f32_16x16x32_f16 v[46:49], v[142:145], v[186:189], v[46:49]
	v_mfma_f32_16x16x32_f16 v[42:45], v[156:159], v[186:189], v[42:45]
	v_mfma_f32_16x16x32_f16 v[30:33], v[142:145], v[194:197], v[30:33]
	v_mfma_f32_16x16x32_f16 v[26:29], v[156:159], v[194:197], v[26:29]
	v_mfma_f32_16x16x32_f16 v[14:17], v[142:145], v[202:205], v[14:17]
	v_mfma_f32_16x16x32_f16 v[10:13], v[156:159], v[202:205], v[10:13]
	v_mfma_f32_16x16x32_f16 v[62:65], v[152:155], v[182:185], v[62:65]
	v_mfma_f32_16x16x32_f16 v[58:61], v[174:177], v[182:185], v[58:61]
	v_mfma_f32_16x16x32_f16 v[46:49], v[152:155], v[190:193], v[46:49]
	v_mfma_f32_16x16x32_f16 v[42:45], v[174:177], v[190:193], v[42:45]
	v_mfma_f32_16x16x32_f16 v[30:33], v[152:155], v[198:201], v[30:33]
	v_mfma_f32_16x16x32_f16 v[26:29], v[174:177], v[198:201], v[26:29]
	v_mfma_f32_16x16x32_f16 v[14:17], v[152:155], v[206:209], v[14:17]
	v_mfma_f32_16x16x32_f16 v[10:13], v[174:177], v[206:209], v[10:13]
	s_barrier
	s_add_u32 s22, s34, 0x80080
	s_addc_u32 s23, s35, 0
	s_add_i32 s34, s36, s19
	s_mov_b32 m0, s34
	s_nop 0
	global_load_lds_dwordx4 v134, s[22:23]
	s_add_i32 m0, s34, 0x2000
	s_nop 0
	global_load_lds_dwordx4 v130, s[22:23]
	s_waitcnt vmcnt(6)
	s_barrier
	v_mfma_f32_16x16x32_f16 v[54:57], v[210:213], v[178:181], v[54:57]
	v_mfma_f32_16x16x32_f16 v[50:53], v[238:241], v[178:181], v[50:53]
	v_mfma_f32_16x16x32_f16 v[38:41], v[210:213], v[186:189], v[38:41]
	v_mfma_f32_16x16x32_f16 v[34:37], v[238:241], v[186:189], v[34:37]
	v_mfma_f32_16x16x32_f16 v[22:25], v[210:213], v[194:197], v[22:25]
	v_mfma_f32_16x16x32_f16 v[18:21], v[238:241], v[194:197], v[18:21]
	v_mfma_f32_16x16x32_f16 v[6:9], v[210:213], v[202:205], v[6:9]
	v_mfma_f32_16x16x32_f16 v[2:5], v[238:241], v[202:205], v[2:5]
	v_mfma_f32_16x16x32_f16 v[54:57], v[234:237], v[182:185], v[54:57]
	v_mfma_f32_16x16x32_f16 v[50:53], v[242:245], v[182:185], v[50:53]
	v_mfma_f32_16x16x32_f16 v[38:41], v[234:237], v[190:193], v[38:41]
	v_mfma_f32_16x16x32_f16 v[34:37], v[242:245], v[190:193], v[34:37]
	v_mfma_f32_16x16x32_f16 v[22:25], v[234:237], v[198:201], v[22:25]
	v_mfma_f32_16x16x32_f16 v[18:21], v[242:245], v[198:201], v[18:21]
	v_mfma_f32_16x16x32_f16 v[6:9], v[234:237], v[206:209], v[6:9]
	v_mfma_f32_16x16x32_f16 v[2:5], v[242:245], v[206:209], v[2:5]
	s_add_i32 s58, s58, 2
	s_add_u32 s25, s25, 0x100
	s_addc_u32 s53, s53, 0
	s_add_u32 s6, s6, 0x100
	s_addc_u32 s7, s7, 0
	s_cmp_gt_u32 s58, 29
	s_barrier
	s_cbranch_scc0 .LBB0_302
	s_cmp_lt_i32 s51, 8
	s_cselect_b64 s[34:35], -1, 0
	s_cmp_gt_i32 s51, 7
	s_cbranch_scc1 .LBB0_305
	v_mul_f32_e32 v143, 0x3d372713, v122
	v_mul_f32_e32 v143, v122, v143
	v_fma_f32 v143, v122, v143, v122
	v_mul_f32_e32 v143, 0xbfcc422a, v143
	v_mul_f32_e32 v143, 0x3fb8aa3b, v143
	v_exp_f32_e32 v143, v143
	v_mul_f32_e32 v142, 0x3d372713, v126
	v_mul_f32_e32 v142, v126, v142
	v_fma_f32 v142, v126, v142, v126
	v_add_f32_e32 v143, 1.0, v143
	v_rcp_f32_e32 v144, v143
	v_mul_f32_e32 v143, 0x3d372713, v127
	v_mul_f32_e32 v143, v127, v143
	v_fma_f32 v143, v127, v143, v127
	v_mul_f32_e32 v142, 0xbfcc422a, v142
	v_mul_f32_e32 v143, 0xbfcc422a, v143
	v_mul_f32_e32 v142, 0x3fb8aa3b, v142
	v_mul_f32_e32 v143, 0x3fb8aa3b, v143
	v_mul_f32_e32 v147, 0x3d372713, v124
	v_exp_f32_e32 v142, v142
	v_exp_f32_e32 v143, v143
	v_mul_f32_e32 v147, v124, v147
	v_fma_f32 v147, v124, v147, v124
	v_mul_f32_e32 v147, 0xbfcc422a, v147
	v_mul_f32_e32 v147, 0x3fb8aa3b, v147
	v_add_f32_e32 v142, 1.0, v142
	v_add_f32_e32 v143, 1.0, v143
	v_exp_f32_e32 v147, v147
	v_rcp_f32_e32 v142, v142
	v_rcp_f32_e32 v143, v143
	v_mul_f32_e32 v145, 0x3d372713, v123
	v_add_f32_e32 v147, 1.0, v147
	v_mul_f32_e32 v146, 0x3d372713, v128
	v_rcp_f32_e32 v152, v147
	v_mul_f32_e32 v147, 0x3d372713, v129
	v_pk_mul_f32 v[126:127], v[126:127], v[142:143]
	v_mul_f32_e32 v142, 0x3d372713, v125
	v_mul_f32_e32 v145, v123, v145
	v_mul_f32_e32 v146, v128, v146
	v_mul_f32_e32 v147, v129, v147
	v_mul_f32_e32 v142, v125, v142
	v_fma_f32 v145, v123, v145, v123
	v_fma_f32 v146, v128, v146, v128
	v_fma_f32 v147, v129, v147, v129
	v_fma_f32 v142, v125, v142, v125
	v_mul_f32_e32 v145, 0xbfcc422a, v145
	v_mul_f32_e32 v146, 0xbfcc422a, v146
	v_mul_f32_e32 v147, 0xbfcc422a, v147
	v_mul_f32_e32 v142, 0xbfcc422a, v142
	v_mul_f32_e32 v145, 0x3fb8aa3b, v145
	v_mul_f32_e32 v146, 0x3fb8aa3b, v146
	v_mul_f32_e32 v147, 0x3fb8aa3b, v147
	v_mul_f32_e32 v142, 0x3fb8aa3b, v142
	v_exp_f32_e32 v145, v145
	v_exp_f32_e32 v146, v146
	v_exp_f32_e32 v147, v147
	v_exp_f32_e32 v142, v142
	v_add_f32_e32 v145, 1.0, v145
	v_add_f32_e32 v146, 1.0, v146
	v_add_f32_e32 v147, 1.0, v147
	v_add_f32_e32 v142, 1.0, v142
	v_rcp_f32_e32 v145, v145
	v_rcp_f32_e32 v146, v146
	v_rcp_f32_e32 v147, v147
	v_rcp_f32_e32 v153, v142
	v_pk_mul_f32 v[122:123], v[122:123], v[144:145]
	v_pk_mul_f32 v[128:129], v[128:129], v[146:147]
	v_pk_mul_f32 v[124:125], v[124:125], v[152:153]

;     __device__ __forceinline__ void prefetch(const Unit& u, int wr, int wc, int lane) const { lnfold_prefetch(vl, stats, gW, bW, u, wr, wc, lane); }
;     __device__ __forceinline__ void prefetch(const Unit& u, int wr, int wc, int lane) const { lnfold_prefetch(vl, stats, gW, bW, u, wr, wc, lane); }
; #define PG8_STAGE(bufoff, gbase, voff) do { _Pragma("unroll") for (int _i = 0; _i < 2; ++_i) \
;         __builtin_amdgcn_global_load_lds((const unsigned*)((const char*)(gbase) + (voff)[_i]), (LAS unsigned*)(lds + (bufoff) + ldsw + _i * 8192), 16, 0, 0); } while (0)
; #define PG8_LDA(dst, b, h) do { _Pragma("unroll") for (int m = 0; m < 4; ++m) _Pragma("unroll") for (int k = 0; k < 2; ++k) dst[m][k] = *(const LAS f16x8*)(lds + PG8_SA(b, h) + aoff + m * 2048 + k * 1024); } while (0)
; #define PG8_LDB(dst, b, h) do { _Pragma("unroll") for (int n = 0; n < 2; ++n) _Pragma("unroll") for (int k = 0; k < 2; ++k) dst[n][k] = *(const LAS f16x8*)(lds + PG8_SB(b, h) + boff + n * 2048 + k * 1024); } while (0)
; template <class Epi>
; __device__ __forceinline__ void gemm_phase(LAS unsigned char* lds, const Gemm g0, const StaticOrder& S, const Epi& E) {
;     ...
;         const char* nA = has_next ? (const char*)g.A + (size_t)nxt.pm * tstep : cA; const char* nB = has_next ? (const char*)g.Bt + (size_t)nxt.pn * tstep : cB;
;         for (int t = 0; t < nt; t += 2) {
;             const bool last = (t == nt - 2);
;             if (Epi::PREF && last) E.prefetch(cur, wr, wc, lane);
;             const char* a1 = cA + (size_t)(t + 1) * kstep;
;             const char* a2 = last ? nA : cA + (size_t)(t + 2) * kstep; const char* b2 = last ? nB : cB + (size_t)(t + 2) * kstep;
;             const char* a3 = a2 + kstep; const char* b3 = b2 + kstep;
;             PG8_LDB(B0, 0, 0); PG8_SCHED; PG8_LDA(At, 0, 0); PG8_STAGE(PG8_SA(1, 1), a1 + hstep, voffA);
;             PG8_WAIT_L(8); PG8_BAR; PG8_WAIT_L(0); PG8_MMA(0, 0, At, B0); PG8_BAR; PG8_SCHED;
;             PG8_LDB(B1, 0, 1); PG8_STAGE(PG8_SB(0, 0), b2, voffB);
;             PG8_BAR; PG8_WAIT_L(0); PG8_MMA(0, 1, At, B1); PG8_BAR;
;             PG8_LDA(At, 0, 1); PG8_STAGE(PG8_SA(0, 0), a2, voffA);
;             PG8_BAR; PG8_WAIT_L(0); PG8_MMA(1, 0, At, B0); PG8_BAR; PG8_SCHED;
;             PG8_STAGE(PG8_SB(0, 1), b2 + hstep, voffB);
;             PG8_WAIT_V(6); PG8_BAR; PG8_MMA(1, 1, At, B1); PG8_BAR;
.LBB0_512:
	s_add_u32 s23, s12, 0xfff80080
	s_addc_u32 s48, s13, -1
	s_add_i32 s90, 0, 0x10000
	v_add_u32_e32 v142, s90, v205
	ds_read_b128 v[122:125], v142
	ds_read_b128 v[126:129], v142 offset:1024
	ds_read_b128 v[138:141], v142 offset:2048
	ds_read_b128 v[142:145], v142 offset:3072
	s_cmp_eq_u32 s22, 28
	s_cselect_b32 s51, s15, s48
	s_cselect_b32 s50, s24, s23
	s_cselect_b32 s49, s25, vcc_hi
	s_cselect_b32 s48, s53, vcc_lo
	s_add_i32 m0, s71, 0xc000
	ds_read_b128 v[146:149], v210
	ds_read_b128 v[150:153], v210 offset:1024
	ds_read_b128 v[154:157], v210 offset:2048
	ds_read_b128 v[158:161], v210 offset:3072
	ds_read_b128 v[188:191], v210 offset:4096
	ds_read_b128 v[192:195], v210 offset:5120
	ds_read_b128 v[196:199], v210 offset:6144
	ds_read_b128 v[200:203], v210 offset:7168
	global_load_lds_dwordx4 v186, s[12:13]
	s_add_i32 m0, s71, 0xe000
	s_nop 0
	global_load_lds_dwordx4 v184, s[12:13]
	s_waitcnt lgkmcnt(8)
	s_barrier
	s_waitcnt lgkmcnt(0)
	s_waitcnt lgkmcnt(0)
	v_mfma_f32_16x16x32_f16 v[134:137], v[122:125], v[146:149], v[134:137]
	v_mfma_f32_16x16x32_f16 v[130:133], v[138:141], v[146:149], v[130:133]
	v_mfma_f32_16x16x32_f16 v[110:113], v[122:125], v[154:157], v[110:113]
	v_mfma_f32_16x16x32_f16 v[106:109], v[138:141], v[154:157], v[106:109]
	v_mfma_f32_16x16x32_f16 v[94:97], v[122:125], v[188:191], v[94:97]
	v_mfma_f32_16x16x32_f16 v[90:93], v[138:141], v[188:191], v[90:93]
	v_mfma_f32_16x16x32_f16 v[78:81], v[122:125], v[196:199], v[78:81]
	v_mfma_f32_16x16x32_f16 v[74:77], v[138:141], v[196:199], v[74:77]
	v_mfma_f32_16x16x32_f16 v[134:137], v[126:129], v[150:153], v[134:137]
	v_mfma_f32_16x16x32_f16 v[130:133], v[142:145], v[150:153], v[130:133]
	v_mfma_f32_16x16x32_f16 v[110:113], v[126:129], v[158:161], v[110:113]
	v_mfma_f32_16x16x32_f16 v[106:109], v[142:145], v[158:161], v[106:109]
	v_mfma_f32_16x16x32_f16 v[94:97], v[126:129], v[192:195], v[94:97]
	v_mfma_f32_16x16x32_f16 v[90:93], v[142:145], v[192:195], v[90:93]
	v_mfma_f32_16x16x32_f16 v[78:81], v[126:129], v[200:203], v[78:81]
	v_mfma_f32_16x16x32_f16 v[74:77], v[142:145], v[200:203], v[74:77]
	s_barrier
	s_add_i32 s23, 0, 0x14000
	v_add_u32_e32 v162, s23, v205
	s_add_i32 s90, s90, s75
	ds_read_b128 v[212:215], v162
	ds_read_b128 v[234:237], v162 offset:1024
	ds_read_b128 v[238:241], v162 offset:2048
	ds_read_b128 v[242:245], v162 offset:3072
	v_add_u32_e32 v162, 0x80, v178
	s_mov_b32 m0, s90
	v_add_u32_e32 v164, 0x80, v174
	global_load_lds_dwordx4 v178, s[48:49]
	s_add_i32 m0, s90, 0x2000
	s_nop 0
	global_load_lds_dwordx4 v174, s[48:49]
	s_barrier
	s_waitcnt lgkmcnt(0)
	s_waitcnt lgkmcnt(0)
	v_mfma_f32_16x16x32_f16 v[118:121], v[212:215], v[146:149], v[118:121]
	v_mfma_f32_16x16x32_f16 v[114:117], v[238:241], v[146:149], v[114:117]
	v_mfma_f32_16x16x32_f16 v[102:105], v[212:215], v[154:157], v[102:105]
	v_mfma_f32_16x16x32_f16 v[98:101], v[238:241], v[154:157], v[98:101]
	v_mfma_f32_16x16x32_f16 v[86:89], v[212:215], v[188:191], v[86:89]
	v_mfma_f32_16x16x32_f16 v[82:85], v[238:241], v[188:191], v[82:85]
	v_mfma_f32_16x16x32_f16 v[70:73], v[212:215], v[196:199], v[70:73]
	v_mfma_f32_16x16x32_f16 v[66:69], v[238:241], v[196:199], v[66:69]
	v_mfma_f32_16x16x32_f16 v[118:121], v[234:237], v[150:153], v[118:121]
	v_mfma_f32_16x16x32_f16 v[114:117], v[242:245], v[150:153], v[114:117]
	v_mfma_f32_16x16x32_f16 v[102:105], v[234:237], v[158:161], v[102:105]
	v_mfma_f32_16x16x32_f16 v[98:101], v[242:245], v[158:161], v[98:101]
	v_mfma_f32_16x16x32_f16 v[86:89], v[234:237], v[192:195], v[86:89]
	v_mfma_f32_16x16x32_f16 v[82:85], v[242:245], v[192:195], v[82:85]
	v_mfma_f32_16x16x32_f16 v[70:73], v[234:237], v[200:203], v[70:73]
	v_mfma_f32_16x16x32_f16 v[66:69], v[242:245], v[200:203], v[66:69]
	s_mov_b32 m0, s71
	v_lshl_add_u64 v[170:171], s[50:51], 0, v[180:181]
	s_barrier
	ds_read_b128 v[146:149], v210 offset:16384
	ds_read_b128 v[150:153], v210 offset:17408
	ds_read_b128 v[154:157], v210 offset:18432
	ds_read_b128 v[158:161], v210 offset:19456
	ds_read_b128 v[188:191], v210 offset:20480
	ds_read_b128 v[192:195], v210 offset:21504
	ds_read_b128 v[196:199], v210 offset:22528
	ds_read_b128 v[200:203], v210 offset:23552
	global_load_lds_dwordx4 v[170:171], off
	v_lshl_add_u64 v[172:173], s[50:51], 0, v[176:177]
	s_mov_b32 m0, s61
	s_nop 0
	global_load_lds_dwordx4 v[172:173], off
	s_barrier
	s_waitcnt lgkmcnt(0)
	s_waitcnt lgkmcnt(0)
	v_mfma_f32_16x16x32_f16 v[62:65], v[122:125], v[146:149], v[62:65]
	v_mfma_f32_16x16x32_f16 v[58:61], v[138:141], v[146:149], v[58:61]
	v_mfma_f32_16x16x32_f16 v[46:49], v[122:125], v[154:157], v[46:49]
	v_mfma_f32_16x16x32_f16 v[42:45], v[138:141], v[154:157], v[42:45]
	v_mfma_f32_16x16x32_f16 v[30:33], v[122:125], v[188:191], v[30:33]
	v_mfma_f32_16x16x32_f16 v[26:29], v[138:141], v[188:191], v[26:29]
	v_mfma_f32_16x16x32_f16 v[14:17], v[122:125], v[196:199], v[14:17]
	v_mfma_f32_16x16x32_f16 v[10:13], v[138:141], v[196:199], v[10:13]
	v_mfma_f32_16x16x32_f16 v[62:65], v[126:129], v[150:153], v[62:65]
	v_mfma_f32_16x16x32_f16 v[58:61], v[142:145], v[150:153], v[58:61]
	v_mfma_f32_16x16x32_f16 v[46:49], v[126:129], v[158:161], v[46:49]
	v_mfma_f32_16x16x32_f16 v[42:45], v[142:145], v[158:161], v[42:45]
	v_mfma_f32_16x16x32_f16 v[30:33], v[126:129], v[192:195], v[30:33]
	v_mfma_f32_16x16x32_f16 v[26:29], v[142:145], v[192:195], v[26:29]
	v_mfma_f32_16x16x32_f16 v[14:17], v[126:129], v[200:203], v[14:17]
	v_mfma_f32_16x16x32_f16 v[10:13], v[142:145], v[200:203], v[10:13]
	s_barrier
	s_add_u32 s90, s48, 0x80000
	s_addc_u32 s91, s49, 0
	s_add_i32 s23, s23, s75
	s_mov_b32 m0, s23
	s_nop 0
	global_load_lds_dwordx4 v178, s[90:91]
	s_add_i32 m0, s23, 0x2000
	s_nop 0
	global_load_lds_dwordx4 v174, s[90:91]
	s_waitcnt vmcnt(6)
	s_barrier
; #define PG8_STAGE(bufoff, gbase, voff) do { _Pragma("unroll") for (int _i = 0; _i < 2; ++_i) \
;         __builtin_amdgcn_global_load_lds((const unsigned*)((const char*)(gbase) + (voff)[_i]), (LAS unsigned*)(lds + (bufoff) + ldsw + _i * 8192), 16, 0, 0); } while (0)
; #define PG8_LDA(dst, b, h) do { _Pragma("unroll") for (int m = 0; m < 4; ++m) _Pragma("unroll") for (int k = 0; k < 2; ++k) dst[m][k] = *(const LAS f16x8*)(lds + PG8_SA(b, h) + aoff + m * 2048 + k * 1024); } while (0)
; #define PG8_LDB(dst, b, h) do { _Pragma("unroll") for (int n = 0; n < 2; ++n) _Pragma("unroll") for (int k = 0; k < 2; ++k) dst[n][k] = *(const LAS f16x8*)(lds + PG8_SB(b, h) + boff + n * 2048 + k * 1024); } while (0)
; #define PG8_MMA(ai, bj, At, Bt) do { __builtin_amdgcn_s_setprio(1); _Pragma("unroll") for (int m = 0; m < 4; ++m) _Pragma("unroll") for (int n = 0; n < 2; ++n) _Pragma("unroll") for (int k = 0; k < 2; ++k) \
;         acc[ai][bj][m][n] = __builtin_amdgcn_mfma_f32_16x16x32_f16(Bt[n][k], At[m][k], acc[ai][bj][m][n], 0, 0, 0); __builtin_amdgcn_s_setprio(0); } while (0)
; #define PG8_WAIT_V(n) asm volatile("s_waitcnt vmcnt(" #n ")" ::: "memory")
; #define PG8_WAIT_L(n) asm volatile("s_waitcnt lgkmcnt(" #n ")" ::: "memory")
; #define PG8_BAR __builtin_amdgcn_s_barrier()
; #define PG8_SCHED __builtin_amdgcn_sched_barrier(0)
; template <class Epi>
; __device__ __forceinline__ void gemm_phase(LAS unsigned char* lds, const Gemm g0, const StaticOrder& S, const Epi& E) {
;     ...
;             PG8_WAIT_V(6); PG8_BAR; PG8_MMA(1, 1, At, B1); PG8_BAR;
;             PG8_LDB(B0, 1, 0); PG8_SCHED; PG8_LDA(At, 1, 0); PG8_STAGE(PG8_SA(0, 1), a2 + hstep, voffA);
;             PG8_WAIT_L(8); PG8_BAR; PG8_WAIT_L(0); PG8_MMA(0, 0, At, B0); PG8_BAR; PG8_SCHED;
;             PG8_LDB(B1, 1, 1); PG8_STAGE(PG8_SB(1, 0), b3, voffB);
;             PG8_BAR; PG8_WAIT_L(0); PG8_MMA(0, 1, At, B1); PG8_BAR;
	v_mfma_f32_16x16x32_f16 v[54:57], v[212:215], v[146:149], v[54:57]
	v_mfma_f32_16x16x32_f16 v[50:53], v[238:241], v[146:149], v[50:53]
	v_mfma_f32_16x16x32_f16 v[38:41], v[212:215], v[154:157], v[38:41]
	v_mfma_f32_16x16x32_f16 v[34:37], v[238:241], v[154:157], v[34:37]
	v_mfma_f32_16x16x32_f16 v[22:25], v[212:215], v[188:191], v[22:25]
	v_mfma_f32_16x16x32_f16 v[18:21], v[238:241], v[188:191], v[18:21]
	v_mfma_f32_16x16x32_f16 v[6:9], v[212:215], v[196:199], v[6:9]
	v_mfma_f32_16x16x32_f16 v[2:5], v[238:241], v[196:199], v[2:5]
	v_mfma_f32_16x16x32_f16 v[54:57], v[234:237], v[150:153], v[54:57]
	v_mfma_f32_16x16x32_f16 v[50:53], v[242:245], v[150:153], v[50:53]
	v_mfma_f32_16x16x32_f16 v[38:41], v[234:237], v[158:161], v[38:41]
	v_mfma_f32_16x16x32_f16 v[34:37], v[242:245], v[158:161], v[34:37]
	v_mfma_f32_16x16x32_f16 v[22:25], v[234:237], v[192:195], v[22:25]
	v_mfma_f32_16x16x32_f16 v[18:21], v[242:245], v[192:195], v[18:21]
	v_mfma_f32_16x16x32_f16 v[6:9], v[234:237], v[200:203], v[6:9]
	v_mfma_f32_16x16x32_f16 v[2:5], v[242:245], v[200:203], v[2:5]
	s_add_i32 s23, 0, 0x18000
	v_add_u32_e32 v142, s23, v205
	s_barrier
	ds_read_b128 v[122:125], v142
	ds_read_b128 v[126:129], v142 offset:1024
	ds_read_b128 v[138:141], v142 offset:2048
	ds_read_b128 v[142:145], v142 offset:3072
	s_add_u32 s50, s50, 0x80000
	s_addc_u32 s51, s51, 0
	s_mov_b32 m0, s74
	ds_read_b128 v[146:149], v210 offset:32768
	ds_read_b128 v[150:153], v210 offset:33792
	ds_read_b128 v[154:157], v210 offset:34816
	ds_read_b128 v[158:161], v210 offset:35840
	ds_read_b128 v[188:191], v210 offset:36864
	ds_read_b128 v[192:195], v210 offset:37888
	ds_read_b128 v[196:199], v210 offset:38912
	ds_read_b128 v[200:203], v210 offset:39936
	global_load_lds_dwordx4 v180, s[50:51]
	s_mov_b32 m0, s18
	s_nop 0
	global_load_lds_dwordx4 v176, s[50:51]
	s_waitcnt lgkmcnt(8)
	s_barrier
	s_waitcnt lgkmcnt(0)
	s_waitcnt lgkmcnt(0)
	v_mfma_f32_16x16x32_f16 v[134:137], v[122:125], v[146:149], v[134:137]
	v_mfma_f32_16x16x32_f16 v[130:133], v[138:141], v[146:149], v[130:133]
	v_mfma_f32_16x16x32_f16 v[110:113], v[122:125], v[154:157], v[110:113]
	v_mfma_f32_16x16x32_f16 v[106:109], v[138:141], v[154:157], v[106:109]
	v_mfma_f32_16x16x32_f16 v[94:97], v[122:125], v[188:191], v[94:97]
	v_mfma_f32_16x16x32_f16 v[90:93], v[138:141], v[188:191], v[90:93]
	v_mfma_f32_16x16x32_f16 v[78:81], v[122:125], v[196:199], v[78:81]
	v_mfma_f32_16x16x32_f16 v[74:77], v[138:141], v[196:199], v[74:77]
	v_mfma_f32_16x16x32_f16 v[134:137], v[126:129], v[150:153], v[134:137]
	v_mfma_f32_16x16x32_f16 v[130:133], v[142:145], v[150:153], v[130:133]
	v_mfma_f32_16x16x32_f16 v[110:113], v[126:129], v[158:161], v[110:113]
	v_mfma_f32_16x16x32_f16 v[106:109], v[142:145], v[158:161], v[106:109]
	v_mfma_f32_16x16x32_f16 v[94:97], v[126:129], v[192:195], v[94:97]
	v_mfma_f32_16x16x32_f16 v[90:93], v[142:145], v[192:195], v[90:93]
	v_mfma_f32_16x16x32_f16 v[78:81], v[126:129], v[200:203], v[78:81]
	v_mfma_f32_16x16x32_f16 v[74:77], v[142:145], v[200:203], v[74:77]
	s_barrier
	s_add_i32 s50, 0, 0x1c000
	s_add_i32 s23, s23, s75
	v_add_u32_e32 v211, s50, v205
	s_mov_b32 m0, s23
	ds_read_b128 v[212:215], v211
	ds_read_b128 v[234:237], v211 offset:1024
	ds_read_b128 v[238:241], v211 offset:2048
	ds_read_b128 v[242:245], v211 offset:3072
	global_load_lds_dwordx4 v162, s[48:49]
	s_add_i32 m0, s23, 0x2000
	s_nop 0
	global_load_lds_dwordx4 v164, s[48:49]
	s_barrier
	s_waitcnt lgkmcnt(0)
	s_waitcnt lgkmcnt(0)
	v_mfma_f32_16x16x32_f16 v[118:121], v[212:215], v[146:149], v[118:121]
	v_mfma_f32_16x16x32_f16 v[114:117], v[238:241], v[146:149], v[114:117]
	v_mfma_f32_16x16x32_f16 v[102:105], v[212:215], v[154:157], v[102:105]
	v_mfma_f32_16x16x32_f16 v[98:101], v[238:241], v[154:157], v[98:101]
	v_mfma_f32_16x16x32_f16 v[86:89], v[212:215], v[188:191], v[86:89]
	v_mfma_f32_16x16x32_f16 v[82:85], v[238:241], v[188:191], v[82:85]
	v_mfma_f32_16x16x32_f16 v[70:73], v[212:215], v[196:199], v[70:73]
	v_mfma_f32_16x16x32_f16 v[66:69], v[238:241], v[196:199], v[66:69]
	v_mfma_f32_16x16x32_f16 v[118:121], v[234:237], v[150:153], v[118:121]
	v_mfma_f32_16x16x32_f16 v[114:117], v[242:245], v[150:153], v[114:117]
	v_mfma_f32_16x16x32_f16 v[102:105], v[234:237], v[158:161], v[102:105]
	v_mfma_f32_16x16x32_f16 v[98:101], v[242:245], v[158:161], v[98:101]
	v_mfma_f32_16x16x32_f16 v[86:89], v[234:237], v[192:195], v[86:89]
	v_mfma_f32_16x16x32_f16 v[82:85], v[242:245], v[192:195], v[82:85]
	v_mfma_f32_16x16x32_f16 v[70:73], v[234:237], v[200:203], v[70:73]
	v_mfma_f32_16x16x32_f16 v[66:69], v[242:245], v[200:203], v[66:69]
	s_mov_b32 m0, s28
	v_lshl_add_u64 v[162:163], v[170:171], 0, s[64:65]
	s_barrier
; #define GAS __attribute__((address_space(1)))
; #define PG8_STAGE(bufoff, gbase, voff) do { _Pragma("unroll") for (int _i = 0; _i < 2; ++_i) \
;         __builtin_amdgcn_global_load_lds((const unsigned*)((const char*)(gbase) + (voff)[_i]), (LAS unsigned*)(lds + (bufoff) + ldsw + _i * 8192), 16, 0, 0); } while (0)
; #define PG8_LDA(dst, b, h) do { _Pragma("unroll") for (int m = 0; m < 4; ++m) _Pragma("unroll") for (int k = 0; k < 2; ++k) dst[m][k] = *(const LAS f16x8*)(lds + PG8_SA(b, h) + aoff + m * 2048 + k * 1024); } while (0)
; #define PG8_MMA(ai, bj, At, Bt) do { __builtin_amdgcn_s_setprio(1); _Pragma("unroll") for (int m = 0; m < 4; ++m) _Pragma("unroll") for (int n = 0; n < 2; ++n) _Pragma("unroll") for (int k = 0; k < 2; ++k) \
;         acc[ai][bj][m][n] = __builtin_amdgcn_mfma_f32_16x16x32_f16(Bt[n][k], At[m][k], acc[ai][bj][m][n], 0, 0, 0); __builtin_amdgcn_s_setprio(0); } while (0)
; #define PG8_WAIT_V(n) asm volatile("s_waitcnt vmcnt(" #n ")" ::: "memory")
; #define PG8_WAIT_L(n) asm volatile("s_waitcnt lgkmcnt(" #n ")" ::: "memory")
; #define PG8_BAR __builtin_amdgcn_s_barrier()
; #define PG8_SCHED __builtin_amdgcn_sched_barrier(0)
;     __device__ __forceinline__ void operator()(f32x4 (&acc)[2][2][4][2], const Unit& u, int wr, int wc, int fr, int fq) const {
;     ...
;         { const int lane = fr + 16 * fq, cL = u.pn * BM + wc * 32 + (lane < 32 ? lane : 96 + lane);
;           float vg = 0.f, vb = 0.f, vt = 0.f;
;           if (hasln) { vg = *(const GAS float*)(pg + cL); vb = *(const GAS float*)(pb + cL); }
;           if (haszh) vt = *(const GAS float*)(tg + cL);
; template <class Epi>
; __device__ __forceinline__ void gemm_phase(LAS unsigned char* lds, const Gemm g0, const StaticOrder& S, const Epi& E) {
;     ...
;             PG8_LDA(At, 1, 1); PG8_STAGE(PG8_SA(1, 0), a3, voffA);
;             PG8_BAR; PG8_WAIT_L(0); PG8_MMA(1, 0, At, B0); PG8_BAR; PG8_SCHED;
;             PG8_STAGE(PG8_SB(1, 1), b3 + hstep, voffB);
;             PG8_WAIT_V(6); PG8_BAR; PG8_MMA(1, 1, At, B1); PG8_BAR;
;         }
	ds_read_b128 v[146:149], v210 offset:49152
	ds_read_b128 v[150:153], v210 offset:50176
	ds_read_b128 v[154:157], v210 offset:51200
	ds_read_b128 v[158:161], v210 offset:52224
	ds_read_b128 v[188:191], v210 offset:53248
	ds_read_b128 v[192:195], v210 offset:54272
	ds_read_b128 v[196:199], v210 offset:55296
	ds_read_b128 v[200:203], v210 offset:56320
	global_load_lds_dwordx4 v[162:163], off
	v_lshl_add_u64 v[162:163], v[172:173], 0, s[64:65]
	s_mov_b32 m0, s29
	s_nop 0
	global_load_lds_dwordx4 v[162:163], off
	s_barrier
	s_waitcnt lgkmcnt(0)
	s_waitcnt lgkmcnt(0)
	v_mfma_f32_16x16x32_f16 v[62:65], v[122:125], v[146:149], v[62:65]
	v_mfma_f32_16x16x32_f16 v[58:61], v[138:141], v[146:149], v[58:61]
	v_mfma_f32_16x16x32_f16 v[46:49], v[122:125], v[154:157], v[46:49]
	v_mfma_f32_16x16x32_f16 v[42:45], v[138:141], v[154:157], v[42:45]
	v_mfma_f32_16x16x32_f16 v[30:33], v[122:125], v[188:191], v[30:33]
	v_mfma_f32_16x16x32_f16 v[26:29], v[138:141], v[188:191], v[26:29]
	v_mfma_f32_16x16x32_f16 v[14:17], v[122:125], v[196:199], v[14:17]
	v_mfma_f32_16x16x32_f16 v[10:13], v[138:141], v[196:199], v[10:13]
	v_mfma_f32_16x16x32_f16 v[62:65], v[126:129], v[150:153], v[62:65]
	v_mfma_f32_16x16x32_f16 v[58:61], v[142:145], v[150:153], v[58:61]
	v_mfma_f32_16x16x32_f16 v[46:49], v[126:129], v[158:161], v[46:49]
	v_mfma_f32_16x16x32_f16 v[42:45], v[142:145], v[158:161], v[42:45]
	v_mfma_f32_16x16x32_f16 v[30:33], v[126:129], v[192:195], v[30:33]
	v_mfma_f32_16x16x32_f16 v[26:29], v[142:145], v[192:195], v[26:29]
	v_mfma_f32_16x16x32_f16 v[14:17], v[126:129], v[200:203], v[14:17]
	v_mfma_f32_16x16x32_f16 v[10:13], v[142:145], v[200:203], v[10:13]
	s_barrier
	s_add_u32 s48, s48, 0x80080
	s_addc_u32 s49, s49, 0
	s_add_i32 s23, s50, s75
	s_mov_b32 m0, s23
	s_nop 0
	global_load_lds_dwordx4 v178, s[48:49]
	s_add_i32 m0, s23, 0x2000
	s_nop 0
	global_load_lds_dwordx4 v174, s[48:49]
	s_waitcnt vmcnt(6)
	s_barrier
	v_mfma_f32_16x16x32_f16 v[54:57], v[212:215], v[146:149], v[54:57]
	v_mfma_f32_16x16x32_f16 v[50:53], v[238:241], v[146:149], v[50:53]
	v_mfma_f32_16x16x32_f16 v[38:41], v[212:215], v[154:157], v[38:41]
	v_mfma_f32_16x16x32_f16 v[34:37], v[238:241], v[154:157], v[34:37]
	v_mfma_f32_16x16x32_f16 v[22:25], v[212:215], v[188:191], v[22:25]
	v_mfma_f32_16x16x32_f16 v[18:21], v[238:241], v[188:191], v[18:21]
	v_mfma_f32_16x16x32_f16 v[6:9], v[212:215], v[196:199], v[6:9]
	v_mfma_f32_16x16x32_f16 v[2:5], v[238:241], v[196:199], v[2:5]
	v_mfma_f32_16x16x32_f16 v[54:57], v[234:237], v[150:153], v[54:57]
	v_mfma_f32_16x16x32_f16 v[50:53], v[242:245], v[150:153], v[50:53]
	v_mfma_f32_16x16x32_f16 v[38:41], v[234:237], v[158:161], v[38:41]
	v_mfma_f32_16x16x32_f16 v[34:37], v[242:245], v[158:161], v[34:37]
	v_mfma_f32_16x16x32_f16 v[22:25], v[234:237], v[192:195], v[22:25]
	v_mfma_f32_16x16x32_f16 v[18:21], v[242:245], v[192:195], v[18:21]
	v_mfma_f32_16x16x32_f16 v[6:9], v[234:237], v[200:203], v[6:9]
	v_mfma_f32_16x16x32_f16 v[2:5], v[242:245], v[200:203], v[2:5]
	s_add_i32 s22, s22, 2
	s_add_u32 vcc_lo, vcc_lo, 0x100
	s_addc_u32 vcc_hi, vcc_hi, 0
	s_add_u32 s12, s12, 0x100
	s_addc_u32 s13, s13, 0
	s_cmp_gt_u32 s22, 29
	s_barrier
	s_cbranch_scc0 .LBB0_512
	s_lshl_b32 s12, s83, 8
	s_or_b32 s15, s12, s31
	v_add_u32_e32 v122, s15, v206
	v_cndmask_b32_e64 v124, 0, 1, s[44:45]
	v_ashrrev_i32_e32 v123, 31, v122
	v_mov_b32_e32 v196, 0
	v_cmp_ne_u32_e64 s[12:13], 1, v124
	s_andn2_b64 vcc, exec, s[44:45]
	v_mov_b32_e32 v124, 0
	v_mov_b32_e32 v125, 0
	s_cbranch_vccnz .LBB0_515
	v_lshlrev_b64 v[124:125], 2, v[122:123]
	v_lshl_add_u64 v[126:127], s[80:81], 0, v[124:125]
	v_lshl_add_u64 v[124:125], s[58:59], 0, v[124:125]
	global_load_dword v125, v[124:125], off
	s_nop 0
	global_load_dword v124, v[126:127], off

;     __device__ __forceinline__ void prefetch(const Unit& u, int wr, int wc, int lane) const { lnfold_prefetch(vl, stats, gW, bW, u, wr, wc, lane); }
;     __device__ __forceinline__ void prefetch(const Unit& u, int wr, int wc, int lane) const { lnfold_prefetch(vl, stats, gW, bW, u, wr, wc, lane); }
; #define PG8_STAGE(bufoff, gbase, voff) do { _Pragma("unroll") for (int _i = 0; _i < 2; ++_i) \
;         __builtin_amdgcn_global_load_lds((const unsigned*)((const char*)(gbase) + (voff)[_i]), (LAS unsigned*)(lds + (bufoff) + ldsw + _i * 8192), 16, 0, 0); } while (0)
; #define PG8_LDA(dst, b, h) do { _Pragma("unroll") for (int m = 0; m < 4; ++m) _Pragma("unroll") for (int k = 0; k < 2; ++k) dst[m][k] = *(const LAS f16x8*)(lds + PG8_SA(b, h) + aoff + m * 2048 + k * 1024); } while (0)
; #define PG8_LDB(dst, b, h) do { _Pragma("unroll") for (int n = 0; n < 2; ++n) _Pragma("unroll") for (int k = 0; k < 2; ++k) dst[n][k] = *(const LAS f16x8*)(lds + PG8_SB(b, h) + boff + n * 2048 + k * 1024); } while (0)
; template <class Epi>
; __device__ __forceinline__ void gemm_phase(LAS unsigned char* lds, const Gemm g0, const StaticOrder& S, const Epi& E) {
;     ...
;         const char* nA = has_next ? (const char*)g.A + (size_t)nxt.pm * tstep : cA; const char* nB = has_next ? (const char*)g.Bt + (size_t)nxt.pn * tstep : cB;
;         for (int t = 0; t < nt; t += 2) {
;             const bool last = (t == nt - 2);
;             if (Epi::PREF && last) E.prefetch(cur, wr, wc, lane);
;             const char* a1 = cA + (size_t)(t + 1) * kstep;
;             const char* a2 = last ? nA : cA + (size_t)(t + 2) * kstep; const char* b2 = last ? nB : cB + (size_t)(t + 2) * kstep;
;             const char* a3 = a2 + kstep; const char* b3 = b2 + kstep;
;             PG8_LDB(B0, 0, 0); PG8_SCHED; PG8_LDA(At, 0, 0); PG8_STAGE(PG8_SA(1, 1), a1 + hstep, voffA);
;             PG8_WAIT_L(8); PG8_BAR; PG8_WAIT_L(0); PG8_MMA(0, 0, At, B0); PG8_BAR; PG8_SCHED;
;             PG8_LDB(B1, 0, 1); PG8_STAGE(PG8_SB(0, 0), b2, voffB);
;             PG8_BAR; PG8_WAIT_L(0); PG8_MMA(0, 1, At, B1); PG8_BAR;
;             PG8_LDA(At, 0, 1); PG8_STAGE(PG8_SA(0, 0), a2, voffA);
;             PG8_BAR; PG8_WAIT_L(0); PG8_MMA(1, 0, At, B0); PG8_BAR; PG8_SCHED;
;             PG8_STAGE(PG8_SB(0, 1), b2 + hstep, voffB);
;             PG8_WAIT_V(6); PG8_BAR; PG8_MMA(1, 1, At, B1); PG8_BAR;
.LBB0_620:
	s_add_u32 s58, s50, 0xfff80080
	s_addc_u32 s59, s51, -1
	s_and_b64 s[22:23], s[52:53], exec
	s_cselect_b32 s59, s37, s59
	s_cselect_b32 s58, s74, s58
	s_add_i32 s82, 0, 0x10000
	v_add_u32_e32 v68, s82, v189
	ds_read_b128 v[60:63], v68
	ds_read_b128 v[64:67], v68 offset:1024
	ds_read_b128 v[78:81], v68 offset:2048
	ds_read_b128 v[82:85], v68 offset:3072
	s_and_b64 s[22:23], s[52:53], exec
	s_cselect_b32 s53, s35, s25
	s_cselect_b32 s52, s75, s24
	s_add_i32 m0, s18, 0xc000
	ds_read_b128 v[86:89], v213
	ds_read_b128 v[90:93], v213 offset:1024
	ds_read_b128 v[194:197], v213 offset:2048
	ds_read_b128 v[234:237], v213 offset:3072
	ds_read_b128 v[238:241], v213 offset:4096
	ds_read_b128 v[242:245], v213 offset:5120
	ds_read_b128 v[246:249], v213 offset:6144
	ds_read_b128 v[226:229], v213 offset:7168
	global_load_lds_dwordx4 v184, s[50:51]
	s_add_i32 m0, s18, 0xe000
	s_nop 0
	global_load_lds_dwordx4 v182, s[50:51]
	s_waitcnt lgkmcnt(8)
	s_barrier
	s_waitcnt lgkmcnt(0)
	s_waitcnt lgkmcnt(0)
	v_mfma_f32_16x16x32_f16 v[158:161], v[60:63], v[86:89], v[158:161]
	v_mfma_f32_16x16x32_f16 v[150:153], v[78:81], v[86:89], v[150:153]
	v_mfma_f32_16x16x32_f16 v[142:145], v[60:63], v[194:197], v[142:145]
	v_mfma_f32_16x16x32_f16 v[134:137], v[78:81], v[194:197], v[134:137]
	v_mfma_f32_16x16x32_f16 v[126:129], v[60:63], v[238:241], v[126:129]
	v_mfma_f32_16x16x32_f16 v[118:121], v[78:81], v[238:241], v[118:121]
	v_mfma_f32_16x16x32_f16 v[110:113], v[60:63], v[246:249], v[110:113]
	v_mfma_f32_16x16x32_f16 v[102:105], v[78:81], v[246:249], v[102:105]
	v_mfma_f32_16x16x32_f16 v[158:161], v[64:67], v[90:93], v[158:161]
	v_mfma_f32_16x16x32_f16 v[150:153], v[82:85], v[90:93], v[150:153]
	v_mfma_f32_16x16x32_f16 v[142:145], v[64:67], v[234:237], v[142:145]
	v_mfma_f32_16x16x32_f16 v[134:137], v[82:85], v[234:237], v[134:137]
	v_mfma_f32_16x16x32_f16 v[126:129], v[64:67], v[242:245], v[126:129]
	v_mfma_f32_16x16x32_f16 v[118:121], v[82:85], v[242:245], v[118:121]
	v_mfma_f32_16x16x32_f16 v[110:113], v[64:67], v[226:229], v[110:113]
	v_mfma_f32_16x16x32_f16 v[102:105], v[82:85], v[226:229], v[102:105]
	s_barrier
	s_add_i32 s83, 0, 0x14000
	s_add_i32 s22, s82, s5
	v_add_u32_e32 v68, s83, v189
	v_add_u32_e32 v186, 0x80, v178
	s_mov_b32 m0, s22
	ds_read_b128 v[162:165], v68
	ds_read_b128 v[222:225], v68 offset:1024
	ds_read_b128 v[214:217], v68 offset:2048
	ds_read_b128 v[170:173], v68 offset:3072
	global_load_lds_dwordx4 v178, s[52:53]
	v_add_u32_e32 v190, 0x80, v174
	s_add_i32 m0, s22, 0x2000
	s_nop 0
	global_load_lds_dwordx4 v174, s[52:53]
	s_barrier
	s_waitcnt lgkmcnt(0)
	s_waitcnt lgkmcnt(0)
	v_mfma_f32_16x16x32_f16 v[154:157], v[162:165], v[86:89], v[154:157]
	v_mfma_f32_16x16x32_f16 v[86:89], v[214:217], v[86:89], v[146:149]
	v_mfma_f32_16x16x32_f16 v[130:133], v[214:217], v[194:197], v[130:133]
	v_mfma_f32_16x16x32_f16 v[122:125], v[162:165], v[238:241], v[122:125]
	v_mfma_f32_16x16x32_f16 v[114:117], v[214:217], v[238:241], v[114:117]
	v_mfma_f32_16x16x32_f16 v[106:109], v[162:165], v[246:249], v[106:109]
	v_mfma_f32_16x16x32_f16 v[98:101], v[214:217], v[246:249], v[98:101]
	v_mfma_f32_16x16x32_f16 v[154:157], v[222:225], v[90:93], v[154:157]
	v_mfma_f32_16x16x32_f16 v[86:89], v[170:173], v[90:93], v[86:89]
	v_mfma_f32_16x16x32_f16 v[90:93], v[162:165], v[194:197], v[138:141]
	v_mfma_f32_16x16x32_f16 v[130:133], v[170:173], v[234:237], v[130:133]
	v_mfma_f32_16x16x32_f16 v[122:125], v[222:225], v[242:245], v[122:125]
	v_mfma_f32_16x16x32_f16 v[114:117], v[170:173], v[242:245], v[114:117]
	v_mfma_f32_16x16x32_f16 v[106:109], v[222:225], v[226:229], v[106:109]
	v_mfma_f32_16x16x32_f16 v[98:101], v[170:173], v[226:229], v[98:101]
	v_mfma_f32_16x16x32_f16 v[90:93], v[222:225], v[234:237], v[90:93]
	s_mov_b32 m0, s18
	v_lshl_add_u64 v[198:199], s[58:59], 0, v[180:181]
	s_barrier
	ds_read_b128 v[138:141], v213 offset:16384
	ds_read_b128 v[146:149], v213 offset:17408
	ds_read_b128 v[194:197], v213 offset:18432
	ds_read_b128 v[226:229], v213 offset:19456
	ds_read_b128 v[234:237], v213 offset:20480
	ds_read_b128 v[238:241], v213 offset:21504
	ds_read_b128 v[242:245], v213 offset:22528
	ds_read_b128 v[246:249], v213 offset:23552
	global_load_lds_dwordx4 v[198:199], off
	v_lshl_add_u64 v[202:203], s[58:59], 0, v[176:177]
	s_mov_b32 m0, s19
	s_nop 0
	global_load_lds_dwordx4 v[202:203], off
	s_barrier
	s_waitcnt lgkmcnt(0)
	s_waitcnt lgkmcnt(0)
	v_mfma_f32_16x16x32_f16 v[94:97], v[60:63], v[138:141], v[94:97]
	v_mfma_f32_16x16x32_f16 v[68:71], v[78:81], v[138:141], v[70:73]
	v_mfma_f32_16x16x32_f16 v[46:49], v[60:63], v[194:197], v[46:49]
	v_mfma_f32_16x16x32_f16 v[38:41], v[78:81], v[194:197], v[38:41]
	v_mfma_f32_16x16x32_f16 v[30:33], v[60:63], v[234:237], v[30:33]
	v_mfma_f32_16x16x32_f16 v[22:25], v[78:81], v[234:237], v[22:25]
	v_mfma_f32_16x16x32_f16 v[14:17], v[60:63], v[242:245], v[14:17]
	v_mfma_f32_16x16x32_f16 v[6:9], v[78:81], v[242:245], v[6:9]
	v_mfma_f32_16x16x32_f16 v[94:97], v[64:67], v[146:149], v[94:97]
	v_mfma_f32_16x16x32_f16 v[68:71], v[82:85], v[146:149], v[68:71]
	v_mfma_f32_16x16x32_f16 v[46:49], v[64:67], v[226:229], v[46:49]
	v_mfma_f32_16x16x32_f16 v[38:41], v[82:85], v[226:229], v[38:41]
	v_mfma_f32_16x16x32_f16 v[30:33], v[64:67], v[238:241], v[30:33]
	v_mfma_f32_16x16x32_f16 v[22:25], v[82:85], v[238:241], v[22:25]
	v_mfma_f32_16x16x32_f16 v[14:17], v[64:67], v[246:249], v[14:17]
	v_mfma_f32_16x16x32_f16 v[6:9], v[82:85], v[246:249], v[6:9]
	s_barrier
	s_add_u32 s22, s52, 0x80000
	s_addc_u32 s23, s53, 0
	s_add_i32 s82, s83, s5
	s_mov_b32 m0, s82
	s_nop 0
	global_load_lds_dwordx4 v178, s[22:23]
	s_add_i32 m0, s82, 0x2000
	s_nop 0
	global_load_lds_dwordx4 v174, s[22:23]
	s_waitcnt vmcnt(6)
	s_barrier
; #define PG8_STAGE(bufoff, gbase, voff) do { _Pragma("unroll") for (int _i = 0; _i < 2; ++_i) \
;         __builtin_amdgcn_global_load_lds((const unsigned*)((const char*)(gbase) + (voff)[_i]), (LAS unsigned*)(lds + (bufoff) + ldsw + _i * 8192), 16, 0, 0); } while (0)
; #define PG8_LDA(dst, b, h) do { _Pragma("unroll") for (int m = 0; m < 4; ++m) _Pragma("unroll") for (int k = 0; k < 2; ++k) dst[m][k] = *(const LAS f16x8*)(lds + PG8_SA(b, h) + aoff + m * 2048 + k * 1024); } while (0)
; #define PG8_LDB(dst, b, h) do { _Pragma("unroll") for (int n = 0; n < 2; ++n) _Pragma("unroll") for (int k = 0; k < 2; ++k) dst[n][k] = *(const LAS f16x8*)(lds + PG8_SB(b, h) + boff + n * 2048 + k * 1024); } while (0)
; #define PG8_MMA(ai, bj, At, Bt) do { __builtin_amdgcn_s_setprio(1); _Pragma("unroll") for (int m = 0; m < 4; ++m) _Pragma("unroll") for (int n = 0; n < 2; ++n) _Pragma("unroll") for (int k = 0; k < 2; ++k) \
;         acc[ai][bj][m][n] = __builtin_amdgcn_mfma_f32_16x16x32_f16(Bt[n][k], At[m][k], acc[ai][bj][m][n], 0, 0, 0); __builtin_amdgcn_s_setprio(0); } while (0)
; #define PG8_WAIT_V(n) asm volatile("s_waitcnt vmcnt(" #n ")" ::: "memory")
; #define PG8_WAIT_L(n) asm volatile("s_waitcnt lgkmcnt(" #n ")" ::: "memory")
; #define PG8_BAR __builtin_amdgcn_s_barrier()
; #define PG8_SCHED __builtin_amdgcn_sched_barrier(0)
; template <class Epi>
; __device__ __forceinline__ void gemm_phase(LAS unsigned char* lds, const Gemm g0, const StaticOrder& S, const Epi& E) {
;     ...
;             PG8_WAIT_V(6); PG8_BAR; PG8_MMA(1, 1, At, B1); PG8_BAR;
;             PG8_LDB(B0, 1, 0); PG8_SCHED; PG8_LDA(At, 1, 0); PG8_STAGE(PG8_SA(0, 1), a2 + hstep, voffA);
;             PG8_WAIT_L(8); PG8_BAR; PG8_WAIT_L(0); PG8_MMA(0, 0, At, B0); PG8_BAR; PG8_SCHED;
;             PG8_LDB(B1, 1, 1); PG8_STAGE(PG8_SB(1, 0), b3, voffB);
	v_mfma_f32_16x16x32_f16 v[50:53], v[214:217], v[138:141], v[50:53]
	v_mfma_f32_16x16x32_f16 v[42:45], v[162:165], v[194:197], v[42:45]
	v_mfma_f32_16x16x32_f16 v[34:37], v[214:217], v[194:197], v[34:37]
	v_mfma_f32_16x16x32_f16 v[26:29], v[162:165], v[234:237], v[26:29]
	v_mfma_f32_16x16x32_f16 v[18:21], v[214:217], v[234:237], v[18:21]
	v_mfma_f32_16x16x32_f16 v[10:13], v[162:165], v[242:245], v[10:13]
	v_mfma_f32_16x16x32_f16 v[2:5], v[214:217], v[242:245], v[2:5]
	v_mfma_f32_16x16x32_f16 v[60:63], v[162:165], v[138:141], v[74:77]
	v_mfma_f32_16x16x32_f16 v[50:53], v[170:173], v[146:149], v[50:53]
	v_mfma_f32_16x16x32_f16 v[42:45], v[222:225], v[226:229], v[42:45]
	v_mfma_f32_16x16x32_f16 v[34:37], v[170:173], v[226:229], v[34:37]
	v_mfma_f32_16x16x32_f16 v[26:29], v[222:225], v[238:241], v[26:29]
	v_mfma_f32_16x16x32_f16 v[18:21], v[170:173], v[238:241], v[18:21]
	v_mfma_f32_16x16x32_f16 v[10:13], v[222:225], v[246:249], v[10:13]
	v_mfma_f32_16x16x32_f16 v[2:5], v[170:173], v[246:249], v[2:5]
	v_mfma_f32_16x16x32_f16 v[60:63], v[222:225], v[146:149], v[60:63]
	s_add_i32 s82, 0, 0x18000
	v_add_u32_e32 v72, s82, v189
	s_barrier
	ds_read_b128 v[64:67], v72
	ds_read_b128 v[74:77], v72 offset:1024
	ds_read_b128 v[78:81], v72 offset:2048
	ds_read_b128 v[82:85], v72 offset:3072
	s_add_u32 s22, s58, 0x80000
	s_addc_u32 s23, s59, 0
	s_mov_b32 m0, s28
	ds_read_b128 v[138:141], v213 offset:32768
	ds_read_b128 v[146:149], v213 offset:33792
	ds_read_b128 v[162:165], v213 offset:34816
	ds_read_b128 v[170:173], v213 offset:35840
	ds_read_b128 v[194:197], v213 offset:36864
	ds_read_b128 v[214:217], v213 offset:37888
	ds_read_b128 v[222:225], v213 offset:38912
	ds_read_b128 v[226:229], v213 offset:39936
	global_load_lds_dwordx4 v180, s[22:23]
	s_mov_b32 m0, s29
	s_nop 0
	global_load_lds_dwordx4 v176, s[22:23]
	s_waitcnt lgkmcnt(8)
	s_barrier
	s_waitcnt lgkmcnt(0)
	s_waitcnt lgkmcnt(0)
	v_mfma_f32_16x16x32_f16 v[158:161], v[64:67], v[138:141], v[158:161]
	v_mfma_f32_16x16x32_f16 v[150:153], v[78:81], v[138:141], v[150:153]
	v_mfma_f32_16x16x32_f16 v[142:145], v[64:67], v[162:165], v[142:145]
	v_mfma_f32_16x16x32_f16 v[134:137], v[78:81], v[162:165], v[134:137]
	v_mfma_f32_16x16x32_f16 v[126:129], v[64:67], v[194:197], v[126:129]
	v_mfma_f32_16x16x32_f16 v[118:121], v[78:81], v[194:197], v[118:121]
	v_mfma_f32_16x16x32_f16 v[110:113], v[64:67], v[222:225], v[110:113]
	v_mfma_f32_16x16x32_f16 v[102:105], v[78:81], v[222:225], v[102:105]
	v_mfma_f32_16x16x32_f16 v[158:161], v[74:77], v[146:149], v[158:161]
	v_mfma_f32_16x16x32_f16 v[150:153], v[82:85], v[146:149], v[150:153]
	v_mfma_f32_16x16x32_f16 v[142:145], v[74:77], v[170:173], v[142:145]
	v_mfma_f32_16x16x32_f16 v[134:137], v[82:85], v[170:173], v[134:137]
	v_mfma_f32_16x16x32_f16 v[126:129], v[74:77], v[214:217], v[126:129]
	v_mfma_f32_16x16x32_f16 v[118:121], v[82:85], v[214:217], v[118:121]
	v_mfma_f32_16x16x32_f16 v[110:113], v[74:77], v[226:229], v[110:113]
	v_mfma_f32_16x16x32_f16 v[102:105], v[82:85], v[226:229], v[102:105]
	s_barrier
	s_add_i32 s58, 0, 0x1c000
	v_add_u32_e32 v72, s58, v189
	s_add_i32 s22, s82, s5
	ds_read_b128 v[234:237], v72
	ds_read_b128 v[238:241], v72 offset:1024
	ds_read_b128 v[242:245], v72 offset:2048
	ds_read_b128 v[246:249], v72 offset:3072
	s_mov_b32 m0, s22
	s_nop 0
	global_load_lds_dwordx4 v186, s[52:53]
	s_add_i32 m0, s22, 0x2000
	s_nop 0
	global_load_lds_dwordx4 v190, s[52:53]
	s_barrier
; #define PG8_STAGE(bufoff, gbase, voff) do { _Pragma("unroll") for (int _i = 0; _i < 2; ++_i) \
;         __builtin_amdgcn_global_load_lds((const unsigned*)((const char*)(gbase) + (voff)[_i]), (LAS unsigned*)(lds + (bufoff) + ldsw + _i * 8192), 16, 0, 0); } while (0)
; #define PG8_LDA(dst, b, h) do { _Pragma("unroll") for (int m = 0; m < 4; ++m) _Pragma("unroll") for (int k = 0; k < 2; ++k) dst[m][k] = *(const LAS f16x8*)(lds + PG8_SA(b, h) + aoff + m * 2048 + k * 1024); } while (0)
; #define PG8_MMA(ai, bj, At, Bt) do { __builtin_amdgcn_s_setprio(1); _Pragma("unroll") for (int m = 0; m < 4; ++m) _Pragma("unroll") for (int n = 0; n < 2; ++n) _Pragma("unroll") for (int k = 0; k < 2; ++k) \
;         acc[ai][bj][m][n] = __builtin_amdgcn_mfma_f32_16x16x32_f16(Bt[n][k], At[m][k], acc[ai][bj][m][n], 0, 0, 0); __builtin_amdgcn_s_setprio(0); } while (0)
; #define PG8_WAIT_V(n) asm volatile("s_waitcnt vmcnt(" #n ")" ::: "memory")
; #define PG8_WAIT_L(n) asm volatile("s_waitcnt lgkmcnt(" #n ")" ::: "memory")
; #define PG8_BAR __builtin_amdgcn_s_barrier()
; #define PG8_SCHED __builtin_amdgcn_sched_barrier(0)
; template <class Epi>
; __device__ __forceinline__ void gemm_phase(LAS unsigned char* lds, const Gemm g0, const StaticOrder& S, const Epi& E) {
;     ...
;             PG8_BAR; PG8_WAIT_L(0); PG8_MMA(0, 1, At, B1); PG8_BAR;
;             PG8_LDA(At, 1, 1); PG8_STAGE(PG8_SA(1, 0), a3, voffA);
;             PG8_BAR; PG8_WAIT_L(0); PG8_MMA(1, 0, At, B0); PG8_BAR; PG8_SCHED;
;             PG8_STAGE(PG8_SB(1, 1), b3 + hstep, voffB);
;             PG8_WAIT_V(6); PG8_BAR; PG8_MMA(1, 1, At, B1); PG8_BAR;
;         }
	s_waitcnt lgkmcnt(0)
	s_waitcnt lgkmcnt(0)
	v_mfma_f32_16x16x32_f16 v[154:157], v[234:237], v[138:141], v[154:157]
	v_mfma_f32_16x16x32_f16 v[86:89], v[242:245], v[138:141], v[86:89]
	v_mfma_f32_16x16x32_f16 v[154:157], v[238:241], v[146:149], v[154:157]
	v_mfma_f32_16x16x32_f16 v[146:149], v[246:249], v[146:149], v[86:89]
	v_mfma_f32_16x16x32_f16 v[86:89], v[234:237], v[162:165], v[90:93]
	v_mfma_f32_16x16x32_f16 v[138:141], v[238:241], v[170:173], v[86:89]
	v_mfma_f32_16x16x32_f16 v[86:89], v[242:245], v[162:165], v[130:133]
	v_mfma_f32_16x16x32_f16 v[130:133], v[246:249], v[170:173], v[86:89]
	v_mfma_f32_16x16x32_f16 v[86:89], v[234:237], v[194:197], v[122:125]
	v_mfma_f32_16x16x32_f16 v[122:125], v[238:241], v[214:217], v[86:89]
	v_mfma_f32_16x16x32_f16 v[86:89], v[242:245], v[194:197], v[114:117]
	v_mfma_f32_16x16x32_f16 v[114:117], v[246:249], v[214:217], v[86:89]
	v_mfma_f32_16x16x32_f16 v[86:89], v[234:237], v[222:225], v[106:109]
	v_mfma_f32_16x16x32_f16 v[106:109], v[238:241], v[226:229], v[86:89]
	v_mfma_f32_16x16x32_f16 v[86:89], v[242:245], v[222:225], v[98:101]
	v_mfma_f32_16x16x32_f16 v[98:101], v[246:249], v[226:229], v[86:89]
	s_mov_b32 m0, s31
	v_lshl_add_u64 v[72:73], v[198:199], 0, s[64:65]
	s_barrier
	s_nop 2
	ds_read_b128 v[86:89], v213 offset:49152
	ds_read_b128 v[90:93], v213 offset:50176
	ds_read_b128 v[162:165], v213 offset:51200
	ds_read_b128 v[170:173], v213 offset:52224
	ds_read_b128 v[194:197], v213 offset:53248
	ds_read_b128 v[214:217], v213 offset:54272
	ds_read_b128 v[222:225], v213 offset:55296
	ds_read_b128 v[226:229], v213 offset:56320
	global_load_lds_dwordx4 v[72:73], off
	v_lshl_add_u64 v[72:73], v[202:203], 0, s[64:65]
	s_mov_b32 m0, s61
	s_nop 0
	global_load_lds_dwordx4 v[72:73], off
	s_barrier
	s_waitcnt lgkmcnt(0)
	s_waitcnt lgkmcnt(0)
	v_mfma_f32_16x16x32_f16 v[94:97], v[64:67], v[86:89], v[94:97]
	v_mfma_f32_16x16x32_f16 v[68:71], v[78:81], v[86:89], v[68:71]
	v_mfma_f32_16x16x32_f16 v[46:49], v[64:67], v[162:165], v[46:49]
	v_mfma_f32_16x16x32_f16 v[38:41], v[78:81], v[162:165], v[38:41]
	v_mfma_f32_16x16x32_f16 v[30:33], v[64:67], v[194:197], v[30:33]
	v_mfma_f32_16x16x32_f16 v[22:25], v[78:81], v[194:197], v[22:25]
	v_mfma_f32_16x16x32_f16 v[14:17], v[64:67], v[222:225], v[14:17]
	v_mfma_f32_16x16x32_f16 v[6:9], v[78:81], v[222:225], v[6:9]
	v_mfma_f32_16x16x32_f16 v[94:97], v[74:77], v[90:93], v[94:97]
	v_mfma_f32_16x16x32_f16 v[70:73], v[82:85], v[90:93], v[68:71]
	v_mfma_f32_16x16x32_f16 v[46:49], v[74:77], v[170:173], v[46:49]
	v_mfma_f32_16x16x32_f16 v[38:41], v[82:85], v[170:173], v[38:41]
	v_mfma_f32_16x16x32_f16 v[30:33], v[74:77], v[214:217], v[30:33]
	v_mfma_f32_16x16x32_f16 v[22:25], v[82:85], v[214:217], v[22:25]
	v_mfma_f32_16x16x32_f16 v[14:17], v[74:77], v[226:229], v[14:17]
	v_mfma_f32_16x16x32_f16 v[6:9], v[82:85], v[226:229], v[6:9]
	s_barrier
	s_add_u32 s22, s52, 0x80080
	s_addc_u32 s23, s53, 0
	s_add_i32 s52, s58, s5
	s_mov_b32 m0, s52
	s_nop 0
	global_load_lds_dwordx4 v178, s[22:23]
	v_lshl_add_u64 v[64:65], s[22:23], 0, v[174:175]
	s_add_i32 m0, s52, 0x2000
	s_nop 0
	global_load_lds_dwordx4 v[64:65], off
	s_waitcnt vmcnt(6)
	s_barrier
	v_mfma_f32_16x16x32_f16 v[60:63], v[234:237], v[86:89], v[60:63]
	v_mfma_f32_16x16x32_f16 v[50:53], v[242:245], v[86:89], v[50:53]
	v_mfma_f32_16x16x32_f16 v[42:45], v[234:237], v[162:165], v[42:45]
	v_mfma_f32_16x16x32_f16 v[34:37], v[242:245], v[162:165], v[34:37]
	v_mfma_f32_16x16x32_f16 v[26:29], v[234:237], v[194:197], v[26:29]
	v_mfma_f32_16x16x32_f16 v[18:21], v[242:245], v[194:197], v[18:21]
	v_mfma_f32_16x16x32_f16 v[10:13], v[234:237], v[222:225], v[10:13]
	v_mfma_f32_16x16x32_f16 v[2:5], v[242:245], v[222:225], v[2:5]
	v_mfma_f32_16x16x32_f16 v[74:77], v[238:241], v[90:93], v[60:63]
	v_mfma_f32_16x16x32_f16 v[50:53], v[246:249], v[90:93], v[50:53]
	v_mfma_f32_16x16x32_f16 v[42:45], v[238:241], v[170:173], v[42:45]
	v_mfma_f32_16x16x32_f16 v[34:37], v[246:249], v[170:173], v[34:37]
	v_mfma_f32_16x16x32_f16 v[26:29], v[238:241], v[214:217], v[26:29]
	v_mfma_f32_16x16x32_f16 v[18:21], v[246:249], v[214:217], v[18:21]
	v_mfma_f32_16x16x32_f16 v[10:13], v[238:241], v[226:229], v[10:13]
	v_mfma_f32_16x16x32_f16 v[2:5], v[246:249], v[226:229], v[2:5]
	s_add_i32 s81, s81, 2
	s_add_u32 s24, s24, 0x100
	s_addc_u32 s25, s25, 0
	s_add_u32 s50, s50, 0x100
	s_addc_u32 s51, s51, 0
	s_cmp_gt_u32 s81, 29
	s_barrier
	s_cbranch_scc1 .LBB0_616

;     __device__ __forceinline__ void prefetch(const Unit& u, int wr, int wc, int lane) const { lnfold_prefetch(vl, stats, gW, bW, u, wr, wc, lane); }
;     __device__ __forceinline__ void prefetch(const Unit& u, int wr, int wc, int lane) const { lnfold_prefetch(vl, stats, gW, bW, u, wr, wc, lane); }
; #define PG8_STAGE(bufoff, gbase, voff) do { _Pragma("unroll") for (int _i = 0; _i < 2; ++_i) \
;         __builtin_amdgcn_global_load_lds((const unsigned*)((const char*)(gbase) + (voff)[_i]), (LAS unsigned*)(lds + (bufoff) + ldsw + _i * 8192), 16, 0, 0); } while (0)
; #define PG8_LDA(dst, b, h) do { _Pragma("unroll") for (int m = 0; m < 4; ++m) _Pragma("unroll") for (int k = 0; k < 2; ++k) dst[m][k] = *(const LAS f16x8*)(lds + PG8_SA(b, h) + aoff + m * 2048 + k * 1024); } while (0)
; #define PG8_LDB(dst, b, h) do { _Pragma("unroll") for (int n = 0; n < 2; ++n) _Pragma("unroll") for (int k = 0; k < 2; ++k) dst[n][k] = *(const LAS f16x8*)(lds + PG8_SB(b, h) + boff + n * 2048 + k * 1024); } while (0)
; #define PG8_WAIT_V(n) asm volatile("s_waitcnt vmcnt(" #n ")" ::: "memory")
; #define PG8_WAIT_L(n) asm volatile("s_waitcnt lgkmcnt(" #n ")" ::: "memory")
; template <class Epi>
; __device__ __forceinline__ void gemm_phase(LAS unsigned char* lds, const Gemm g0, const StaticOrder& S, const Epi& E) {
;     ...
;         for (int t = 0; t < nt; t += 2) {
;             const bool last = (t == nt - 2);
;             if (Epi::PREF && last) E.prefetch(cur, wr, wc, lane);
;             const char* a1 = cA + (size_t)(t + 1) * kstep;
;             const char* a2 = last ? nA : cA + (size_t)(t + 2) * kstep; const char* b2 = last ? nB : cB + (size_t)(t + 2) * kstep;
;             const char* a3 = a2 + kstep; const char* b3 = b2 + kstep;
;             PG8_LDB(B0, 0, 0); PG8_SCHED; PG8_LDA(At, 0, 0); PG8_STAGE(PG8_SA(1, 1), a1 + hstep, voffA);
;             PG8_WAIT_L(8); PG8_BAR; PG8_WAIT_L(0); PG8_MMA(0, 0, At, B0); PG8_BAR; PG8_SCHED;
;             PG8_LDB(B1, 0, 1); PG8_STAGE(PG8_SB(0, 0), b2, voffB);
;             PG8_BAR; PG8_WAIT_L(0); PG8_MMA(0, 1, At, B1); PG8_BAR;
;             PG8_LDA(At, 0, 1); PG8_STAGE(PG8_SA(0, 0), a2, voffA);
;             PG8_BAR; PG8_WAIT_L(0); PG8_MMA(1, 0, At, B0); PG8_BAR; PG8_SCHED;
;             PG8_STAGE(PG8_SB(0, 1), b2 + hstep, voffB);
;             PG8_WAIT_V(6); PG8_BAR; PG8_MMA(1, 1, At, B1); PG8_BAR;
.LBB0_672:
	s_add_u32 s10, s12, 0x100
	s_addc_u32 s11, s13, 0
	s_add_i32 s23, 0, 0x10000
	v_add_u32_e32 v142, s23, v203
	ds_read_b128 v[130:133], v142
	ds_read_b128 v[134:137], v142 offset:1024
	ds_read_b128 v[138:141], v142 offset:2048
	ds_read_b128 v[142:145], v142 offset:3072
	s_cmpk_eq_i32 s22, 0x54
	s_cselect_b32 s81, s1, s11
	s_cselect_b32 s80, s0, s10
	s_cselect_b32 s63, s59, s25
	s_cselect_b32 s62, s58, s24
	s_add_i32 m0, s28, 0xc000
	ds_read_b128 v[146:149], v208
	ds_read_b128 v[150:153], v208 offset:1024
	ds_read_b128 v[154:157], v208 offset:2048
	ds_read_b128 v[162:165], v208 offset:3072
	ds_read_b128 v[170:173], v208 offset:4096
	ds_read_b128 v[184:187], v208 offset:5120
	ds_read_b128 v[188:191], v208 offset:6144
	ds_read_b128 v[192:195], v208 offset:7168
	global_load_lds_dwordx4 v182, s[12:13]
	s_add_i32 m0, s28, 0xe000
	s_nop 0
	global_load_lds_dwordx4 v180, s[12:13]
	s_waitcnt lgkmcnt(8)
	s_barrier
	s_waitcnt lgkmcnt(0)
	s_waitcnt lgkmcnt(0)
	v_mfma_f32_16x16x32_f16 v[126:129], v[130:133], v[146:149], v[126:129]
	v_mfma_f32_16x16x32_f16 v[122:125], v[138:141], v[146:149], v[122:125]
	v_mfma_f32_16x16x32_f16 v[110:113], v[130:133], v[154:157], v[110:113]
	v_mfma_f32_16x16x32_f16 v[106:109], v[138:141], v[154:157], v[106:109]
	v_mfma_f32_16x16x32_f16 v[94:97], v[130:133], v[170:173], v[94:97]
	v_mfma_f32_16x16x32_f16 v[90:93], v[138:141], v[170:173], v[90:93]
	v_mfma_f32_16x16x32_f16 v[78:81], v[130:133], v[188:191], v[78:81]
	v_mfma_f32_16x16x32_f16 v[74:77], v[138:141], v[188:191], v[74:77]
	v_mfma_f32_16x16x32_f16 v[126:129], v[134:137], v[150:153], v[126:129]
	v_mfma_f32_16x16x32_f16 v[122:125], v[142:145], v[150:153], v[122:125]
	v_mfma_f32_16x16x32_f16 v[110:113], v[134:137], v[162:165], v[110:113]
	v_mfma_f32_16x16x32_f16 v[106:109], v[142:145], v[162:165], v[106:109]
	v_mfma_f32_16x16x32_f16 v[94:97], v[134:137], v[184:187], v[94:97]
	v_mfma_f32_16x16x32_f16 v[90:93], v[142:145], v[184:187], v[90:93]
	v_mfma_f32_16x16x32_f16 v[78:81], v[134:137], v[192:195], v[78:81]
	v_mfma_f32_16x16x32_f16 v[74:77], v[142:145], v[192:195], v[74:77]
	s_barrier
	s_add_i32 s90, 0, 0x14000
	v_add_u32_e32 v200, s90, v203
	s_add_i32 s12, s23, s19
	ds_read_b128 v[196:199], v200
	ds_read_b128 v[210:213], v200 offset:1024
	ds_read_b128 v[214:217], v200 offset:2048
	ds_read_b128 v[222:225], v200 offset:3072
	v_add_u32_e32 v200, 0x80, v174
	s_mov_b32 m0, s12
	v_add_u32_e32 v218, 0x80, v158
	global_load_lds_dwordx4 v174, s[62:63]
	s_add_i32 m0, s12, 0x2000
	s_nop 0
	global_load_lds_dwordx4 v158, s[62:63]
	s_barrier
	s_waitcnt lgkmcnt(0)
	s_waitcnt lgkmcnt(0)
	v_mfma_f32_16x16x32_f16 v[118:121], v[196:199], v[146:149], v[118:121]
	v_mfma_f32_16x16x32_f16 v[114:117], v[214:217], v[146:149], v[114:117]
	v_mfma_f32_16x16x32_f16 v[102:105], v[196:199], v[154:157], v[102:105]
	v_mfma_f32_16x16x32_f16 v[98:101], v[214:217], v[154:157], v[98:101]
	v_mfma_f32_16x16x32_f16 v[86:89], v[196:199], v[170:173], v[86:89]
	v_mfma_f32_16x16x32_f16 v[82:85], v[214:217], v[170:173], v[82:85]
	v_mfma_f32_16x16x32_f16 v[70:73], v[196:199], v[188:191], v[70:73]
	v_mfma_f32_16x16x32_f16 v[66:69], v[214:217], v[188:191], v[66:69]
	v_mfma_f32_16x16x32_f16 v[118:121], v[210:213], v[150:153], v[118:121]
	v_mfma_f32_16x16x32_f16 v[114:117], v[222:225], v[150:153], v[114:117]
	v_mfma_f32_16x16x32_f16 v[102:105], v[210:213], v[162:165], v[102:105]
	v_mfma_f32_16x16x32_f16 v[98:101], v[222:225], v[162:165], v[98:101]
	v_mfma_f32_16x16x32_f16 v[86:89], v[210:213], v[184:187], v[86:89]
	v_mfma_f32_16x16x32_f16 v[82:85], v[222:225], v[184:187], v[82:85]
	v_mfma_f32_16x16x32_f16 v[70:73], v[210:213], v[192:195], v[70:73]
	v_mfma_f32_16x16x32_f16 v[66:69], v[222:225], v[192:195], v[66:69]
	s_mov_b32 m0, s28
	v_lshl_add_u64 v[226:227], s[80:81], 0, v[176:177]
	s_barrier
	ds_read_b128 v[146:149], v208 offset:16384
	ds_read_b128 v[150:153], v208 offset:17408
	ds_read_b128 v[154:157], v208 offset:18432
	ds_read_b128 v[162:165], v208 offset:19456
	ds_read_b128 v[170:173], v208 offset:20480
	ds_read_b128 v[184:187], v208 offset:21504
	ds_read_b128 v[188:191], v208 offset:22528
	ds_read_b128 v[192:195], v208 offset:23552
	global_load_lds_dwordx4 v[226:227], off
	v_lshl_add_u64 v[228:229], s[80:81], 0, v[160:161]
	s_mov_b32 m0, s29
	s_nop 0
	global_load_lds_dwordx4 v[228:229], off
	s_barrier
	s_waitcnt lgkmcnt(0)
	s_waitcnt lgkmcnt(0)
	v_mfma_f32_16x16x32_f16 v[62:65], v[130:133], v[146:149], v[62:65]
	v_mfma_f32_16x16x32_f16 v[58:61], v[138:141], v[146:149], v[58:61]
	v_mfma_f32_16x16x32_f16 v[46:49], v[130:133], v[154:157], v[46:49]
	v_mfma_f32_16x16x32_f16 v[42:45], v[138:141], v[154:157], v[42:45]
	v_mfma_f32_16x16x32_f16 v[30:33], v[130:133], v[170:173], v[30:33]
	v_mfma_f32_16x16x32_f16 v[26:29], v[138:141], v[170:173], v[26:29]
	v_mfma_f32_16x16x32_f16 v[14:17], v[130:133], v[188:191], v[14:17]
	v_mfma_f32_16x16x32_f16 v[10:13], v[138:141], v[188:191], v[10:13]
	v_mfma_f32_16x16x32_f16 v[62:65], v[134:137], v[150:153], v[62:65]
	v_mfma_f32_16x16x32_f16 v[58:61], v[142:145], v[150:153], v[58:61]
	v_mfma_f32_16x16x32_f16 v[46:49], v[134:137], v[162:165], v[46:49]
	v_mfma_f32_16x16x32_f16 v[42:45], v[142:145], v[162:165], v[42:45]
	v_mfma_f32_16x16x32_f16 v[30:33], v[134:137], v[184:187], v[30:33]
	v_mfma_f32_16x16x32_f16 v[26:29], v[142:145], v[184:187], v[26:29]
	v_mfma_f32_16x16x32_f16 v[14:17], v[134:137], v[192:195], v[14:17]
	v_mfma_f32_16x16x32_f16 v[10:13], v[142:145], v[192:195], v[10:13]
	s_barrier
	s_add_u32 s12, s62, 0x160000
	s_addc_u32 s13, s63, 0
	s_add_i32 s23, s90, s19
	s_mov_b32 m0, s23
	s_nop 0
	global_load_lds_dwordx4 v174, s[12:13]
	s_add_i32 m0, s23, 0x2000
	s_nop 0
	global_load_lds_dwordx4 v158, s[12:13]
	s_waitcnt vmcnt(6)
	s_barrier
; #define PG8_STAGE(bufoff, gbase, voff) do { _Pragma("unroll") for (int _i = 0; _i < 2; ++_i) \
;         __builtin_amdgcn_global_load_lds((const unsigned*)((const char*)(gbase) + (voff)[_i]), (LAS unsigned*)(lds + (bufoff) + ldsw + _i * 8192), 16, 0, 0); } while (0)
; #define PG8_LDA(dst, b, h) do { _Pragma("unroll") for (int m = 0; m < 4; ++m) _Pragma("unroll") for (int k = 0; k < 2; ++k) dst[m][k] = *(const LAS f16x8*)(lds + PG8_SA(b, h) + aoff + m * 2048 + k * 1024); } while (0)
; #define PG8_LDB(dst, b, h) do { _Pragma("unroll") for (int n = 0; n < 2; ++n) _Pragma("unroll") for (int k = 0; k < 2; ++k) dst[n][k] = *(const LAS f16x8*)(lds + PG8_SB(b, h) + boff + n * 2048 + k * 1024); } while (0)
; #define PG8_MMA(ai, bj, At, Bt) do { __builtin_amdgcn_s_setprio(1); _Pragma("unroll") for (int m = 0; m < 4; ++m) _Pragma("unroll") for (int n = 0; n < 2; ++n) _Pragma("unroll") for (int k = 0; k < 2; ++k) \
;         acc[ai][bj][m][n] = __builtin_amdgcn_mfma_f32_16x16x32_f16(Bt[n][k], At[m][k], acc[ai][bj][m][n], 0, 0, 0); __builtin_amdgcn_s_setprio(0); } while (0)
; #define PG8_WAIT_V(n) asm volatile("s_waitcnt vmcnt(" #n ")" ::: "memory")
; #define PG8_WAIT_L(n) asm volatile("s_waitcnt lgkmcnt(" #n ")" ::: "memory")
; #define PG8_BAR __builtin_amdgcn_s_barrier()
; #define PG8_SCHED __builtin_amdgcn_sched_barrier(0)
; template <class Epi>
; __device__ __forceinline__ void gemm_phase(LAS unsigned char* lds, const Gemm g0, const StaticOrder& S, const Epi& E) {
;     ...
;             PG8_WAIT_V(6); PG8_BAR; PG8_MMA(1, 1, At, B1); PG8_BAR;
;             PG8_LDB(B0, 1, 0); PG8_SCHED; PG8_LDA(At, 1, 0); PG8_STAGE(PG8_SA(0, 1), a2 + hstep, voffA);
;             PG8_WAIT_L(8); PG8_BAR; PG8_WAIT_L(0); PG8_MMA(0, 0, At, B0); PG8_BAR; PG8_SCHED;
;             PG8_LDB(B1, 1, 1); PG8_STAGE(PG8_SB(1, 0), b3, voffB);
;             PG8_BAR; PG8_WAIT_L(0); PG8_MMA(0, 1, At, B1); PG8_BAR;
	v_mfma_f32_16x16x32_f16 v[54:57], v[196:199], v[146:149], v[54:57]
	v_mfma_f32_16x16x32_f16 v[50:53], v[214:217], v[146:149], v[50:53]
	v_mfma_f32_16x16x32_f16 v[38:41], v[196:199], v[154:157], v[38:41]
	v_mfma_f32_16x16x32_f16 v[34:37], v[214:217], v[154:157], v[34:37]
	v_mfma_f32_16x16x32_f16 v[22:25], v[196:199], v[170:173], v[22:25]
	v_mfma_f32_16x16x32_f16 v[18:21], v[214:217], v[170:173], v[18:21]
	v_mfma_f32_16x16x32_f16 v[6:9], v[196:199], v[188:191], v[6:9]
	v_mfma_f32_16x16x32_f16 v[2:5], v[214:217], v[188:191], v[2:5]
	v_mfma_f32_16x16x32_f16 v[54:57], v[210:213], v[150:153], v[54:57]
	v_mfma_f32_16x16x32_f16 v[50:53], v[222:225], v[150:153], v[50:53]
	v_mfma_f32_16x16x32_f16 v[38:41], v[210:213], v[162:165], v[38:41]
	v_mfma_f32_16x16x32_f16 v[34:37], v[222:225], v[162:165], v[34:37]
	v_mfma_f32_16x16x32_f16 v[22:25], v[210:213], v[184:187], v[22:25]
	v_mfma_f32_16x16x32_f16 v[18:21], v[222:225], v[184:187], v[18:21]
	v_mfma_f32_16x16x32_f16 v[6:9], v[210:213], v[192:195], v[6:9]
	v_mfma_f32_16x16x32_f16 v[2:5], v[222:225], v[192:195], v[2:5]
	s_add_i32 s23, 0, 0x18000
	v_add_u32_e32 v142, s23, v203
	s_barrier
	ds_read_b128 v[130:133], v142
	ds_read_b128 v[134:137], v142 offset:1024
	ds_read_b128 v[138:141], v142 offset:2048
	ds_read_b128 v[142:145], v142 offset:3072
	s_add_u32 s12, s80, 0x160000
	s_addc_u32 s13, s81, 0
	s_mov_b32 m0, s31
	ds_read_b128 v[146:149], v208 offset:32768
	ds_read_b128 v[150:153], v208 offset:33792
	ds_read_b128 v[154:157], v208 offset:34816
	ds_read_b128 v[162:165], v208 offset:35840
	ds_read_b128 v[170:173], v208 offset:36864
	ds_read_b128 v[184:187], v208 offset:37888
	ds_read_b128 v[188:191], v208 offset:38912
	ds_read_b128 v[192:195], v208 offset:39936
	global_load_lds_dwordx4 v176, s[12:13]
	s_mov_b32 m0, s61
	s_nop 0
	global_load_lds_dwordx4 v160, s[12:13]
	s_waitcnt lgkmcnt(8)
	s_barrier
	s_waitcnt lgkmcnt(0)
	s_waitcnt lgkmcnt(0)
	v_mfma_f32_16x16x32_f16 v[126:129], v[130:133], v[146:149], v[126:129]
	v_mfma_f32_16x16x32_f16 v[122:125], v[138:141], v[146:149], v[122:125]
	v_mfma_f32_16x16x32_f16 v[110:113], v[130:133], v[154:157], v[110:113]
	v_mfma_f32_16x16x32_f16 v[106:109], v[138:141], v[154:157], v[106:109]
	v_mfma_f32_16x16x32_f16 v[94:97], v[130:133], v[170:173], v[94:97]
	v_mfma_f32_16x16x32_f16 v[90:93], v[138:141], v[170:173], v[90:93]
	v_mfma_f32_16x16x32_f16 v[78:81], v[130:133], v[188:191], v[78:81]
	v_mfma_f32_16x16x32_f16 v[74:77], v[138:141], v[188:191], v[74:77]
	v_mfma_f32_16x16x32_f16 v[126:129], v[134:137], v[150:153], v[126:129]
	v_mfma_f32_16x16x32_f16 v[122:125], v[142:145], v[150:153], v[122:125]
	v_mfma_f32_16x16x32_f16 v[110:113], v[134:137], v[162:165], v[110:113]
	v_mfma_f32_16x16x32_f16 v[106:109], v[142:145], v[162:165], v[106:109]
	v_mfma_f32_16x16x32_f16 v[94:97], v[134:137], v[184:187], v[94:97]
	v_mfma_f32_16x16x32_f16 v[90:93], v[142:145], v[184:187], v[90:93]
	v_mfma_f32_16x16x32_f16 v[78:81], v[134:137], v[192:195], v[78:81]
	v_mfma_f32_16x16x32_f16 v[74:77], v[142:145], v[192:195], v[74:77]
	s_barrier
	s_add_i32 s80, 0, 0x1c000
	s_add_i32 s12, s23, s19
	v_add_u32_e32 v209, s80, v203
	s_mov_b32 m0, s12
	ds_read_b128 v[196:199], v209
	ds_read_b128 v[210:213], v209 offset:1024
	ds_read_b128 v[214:217], v209 offset:2048
	ds_read_b128 v[222:225], v209 offset:3072
	global_load_lds_dwordx4 v200, s[62:63]
	s_add_i32 m0, s12, 0x2000
	s_nop 0
	global_load_lds_dwordx4 v218, s[62:63]
	s_barrier
	s_waitcnt lgkmcnt(0)
	s_waitcnt lgkmcnt(0)
	v_mfma_f32_16x16x32_f16 v[118:121], v[196:199], v[146:149], v[118:121]
	v_mfma_f32_16x16x32_f16 v[114:117], v[214:217], v[146:149], v[114:117]
	v_mfma_f32_16x16x32_f16 v[102:105], v[196:199], v[154:157], v[102:105]
	v_mfma_f32_16x16x32_f16 v[98:101], v[214:217], v[154:157], v[98:101]
	v_mfma_f32_16x16x32_f16 v[86:89], v[196:199], v[170:173], v[86:89]
	v_mfma_f32_16x16x32_f16 v[82:85], v[214:217], v[170:173], v[82:85]
	v_mfma_f32_16x16x32_f16 v[70:73], v[196:199], v[188:191], v[70:73]
	v_mfma_f32_16x16x32_f16 v[66:69], v[214:217], v[188:191], v[66:69]
	v_mfma_f32_16x16x32_f16 v[118:121], v[210:213], v[150:153], v[118:121]
	v_mfma_f32_16x16x32_f16 v[114:117], v[222:225], v[150:153], v[114:117]
	v_mfma_f32_16x16x32_f16 v[102:105], v[210:213], v[162:165], v[102:105]
	v_mfma_f32_16x16x32_f16 v[98:101], v[222:225], v[162:165], v[98:101]
	v_mfma_f32_16x16x32_f16 v[86:89], v[210:213], v[184:187], v[86:89]
	v_mfma_f32_16x16x32_f16 v[82:85], v[222:225], v[184:187], v[82:85]
	v_mfma_f32_16x16x32_f16 v[70:73], v[210:213], v[192:195], v[70:73]
	v_mfma_f32_16x16x32_f16 v[66:69], v[222:225], v[192:195], v[66:69]
	s_mov_b32 m0, s83
	v_lshl_add_u64 v[200:201], v[226:227], 0, s[64:65]
	s_barrier
; #define GAS __attribute__((address_space(1)))
; #define PG8_STAGE(bufoff, gbase, voff) do { _Pragma("unroll") for (int _i = 0; _i < 2; ++_i) \
;         __builtin_amdgcn_global_load_lds((const unsigned*)((const char*)(gbase) + (voff)[_i]), (LAS unsigned*)(lds + (bufoff) + ldsw + _i * 8192), 16, 0, 0); } while (0)
; #define PG8_LDA(dst, b, h) do { _Pragma("unroll") for (int m = 0; m < 4; ++m) _Pragma("unroll") for (int k = 0; k < 2; ++k) dst[m][k] = *(const LAS f16x8*)(lds + PG8_SA(b, h) + aoff + m * 2048 + k * 1024); } while (0)
; #define PG8_MMA(ai, bj, At, Bt) do { __builtin_amdgcn_s_setprio(1); _Pragma("unroll") for (int m = 0; m < 4; ++m) _Pragma("unroll") for (int n = 0; n < 2; ++n) _Pragma("unroll") for (int k = 0; k < 2; ++k) \
;         acc[ai][bj][m][n] = __builtin_amdgcn_mfma_f32_16x16x32_f16(Bt[n][k], At[m][k], acc[ai][bj][m][n], 0, 0, 0); __builtin_amdgcn_s_setprio(0); } while (0)
; #define PG8_WAIT_V(n) asm volatile("s_waitcnt vmcnt(" #n ")" ::: "memory")
; #define PG8_WAIT_L(n) asm volatile("s_waitcnt lgkmcnt(" #n ")" ::: "memory")
; #define PG8_BAR __builtin_amdgcn_s_barrier()
; #define PG8_SCHED __builtin_amdgcn_sched_barrier(0)
;     __device__ __forceinline__ void operator()(f32x4 (&acc)[2][2][4][2], const Unit& u, int wr, int wc, int fr, int fq) const {
;     ...
;         { const int lane = fr + 16 * fq, cL = u.pn * BM + wc * 32 + (lane < 32 ? lane : 96 + lane);
;           float vg = 0.f, vb = 0.f, vt = 0.f;
;           if (hasln) { vg = *(const GAS float*)(pg + cL); vb = *(const GAS float*)(pb + cL); }
;           if (haszh) vt = *(const GAS float*)(tg + cL);
; template <class Epi>
; __device__ __forceinline__ void gemm_phase(LAS unsigned char* lds, const Gemm g0, const StaticOrder& S, const Epi& E) {
;     ...
;             PG8_LDA(At, 1, 1); PG8_STAGE(PG8_SA(1, 0), a3, voffA);
;             PG8_BAR; PG8_WAIT_L(0); PG8_MMA(1, 0, At, B0); PG8_BAR; PG8_SCHED;
;             PG8_STAGE(PG8_SB(1, 1), b3 + hstep, voffB);
;             PG8_WAIT_V(6); PG8_BAR; PG8_MMA(1, 1, At, B1); PG8_BAR;
;         }
	ds_read_b128 v[146:149], v208 offset:49152
	ds_read_b128 v[150:153], v208 offset:50176
	ds_read_b128 v[154:157], v208 offset:51200
	ds_read_b128 v[162:165], v208 offset:52224
	ds_read_b128 v[170:173], v208 offset:53248
	ds_read_b128 v[184:187], v208 offset:54272
	ds_read_b128 v[188:191], v208 offset:55296
	ds_read_b128 v[192:195], v208 offset:56320
	global_load_lds_dwordx4 v[200:201], off
	v_lshl_add_u64 v[200:201], v[228:229], 0, s[64:65]
	s_mov_b32 m0, s84
	s_nop 0
	global_load_lds_dwordx4 v[200:201], off
	s_barrier
	s_waitcnt lgkmcnt(0)
	s_waitcnt lgkmcnt(0)
	v_mfma_f32_16x16x32_f16 v[62:65], v[130:133], v[146:149], v[62:65]
	v_mfma_f32_16x16x32_f16 v[58:61], v[138:141], v[146:149], v[58:61]
	v_mfma_f32_16x16x32_f16 v[46:49], v[130:133], v[154:157], v[46:49]
	v_mfma_f32_16x16x32_f16 v[42:45], v[138:141], v[154:157], v[42:45]
	v_mfma_f32_16x16x32_f16 v[30:33], v[130:133], v[170:173], v[30:33]
	v_mfma_f32_16x16x32_f16 v[26:29], v[138:141], v[170:173], v[26:29]
	v_mfma_f32_16x16x32_f16 v[14:17], v[130:133], v[188:191], v[14:17]
	v_mfma_f32_16x16x32_f16 v[10:13], v[138:141], v[188:191], v[10:13]
	v_mfma_f32_16x16x32_f16 v[62:65], v[134:137], v[150:153], v[62:65]
	v_mfma_f32_16x16x32_f16 v[58:61], v[142:145], v[150:153], v[58:61]
	v_mfma_f32_16x16x32_f16 v[46:49], v[134:137], v[162:165], v[46:49]
	v_mfma_f32_16x16x32_f16 v[42:45], v[142:145], v[162:165], v[42:45]
	v_mfma_f32_16x16x32_f16 v[30:33], v[134:137], v[184:187], v[30:33]
	v_mfma_f32_16x16x32_f16 v[26:29], v[142:145], v[184:187], v[26:29]
	v_mfma_f32_16x16x32_f16 v[14:17], v[134:137], v[192:195], v[14:17]
	v_mfma_f32_16x16x32_f16 v[10:13], v[142:145], v[192:195], v[10:13]
	s_barrier
	s_add_u32 s12, s62, 0x160080
	s_addc_u32 s13, s63, 0
	s_add_i32 s23, s80, s19
	s_mov_b32 m0, s23
	s_nop 0
	global_load_lds_dwordx4 v174, s[12:13]
	s_add_i32 m0, s23, 0x2000
	s_nop 0
	global_load_lds_dwordx4 v158, s[12:13]
	s_waitcnt vmcnt(6)
	s_barrier
	v_mfma_f32_16x16x32_f16 v[54:57], v[196:199], v[146:149], v[54:57]
	v_mfma_f32_16x16x32_f16 v[50:53], v[214:217], v[146:149], v[50:53]
	v_mfma_f32_16x16x32_f16 v[38:41], v[196:199], v[154:157], v[38:41]
	v_mfma_f32_16x16x32_f16 v[34:37], v[214:217], v[154:157], v[34:37]
	v_mfma_f32_16x16x32_f16 v[22:25], v[196:199], v[170:173], v[22:25]
	v_mfma_f32_16x16x32_f16 v[18:21], v[214:217], v[170:173], v[18:21]
	v_mfma_f32_16x16x32_f16 v[6:9], v[196:199], v[188:191], v[6:9]
	v_mfma_f32_16x16x32_f16 v[2:5], v[214:217], v[188:191], v[2:5]
	v_mfma_f32_16x16x32_f16 v[54:57], v[210:213], v[150:153], v[54:57]
	v_mfma_f32_16x16x32_f16 v[50:53], v[222:225], v[150:153], v[50:53]
	v_mfma_f32_16x16x32_f16 v[38:41], v[210:213], v[162:165], v[38:41]
	v_mfma_f32_16x16x32_f16 v[34:37], v[222:225], v[162:165], v[34:37]
	v_mfma_f32_16x16x32_f16 v[22:25], v[210:213], v[184:187], v[22:25]
	v_mfma_f32_16x16x32_f16 v[18:21], v[222:225], v[184:187], v[18:21]
	v_mfma_f32_16x16x32_f16 v[6:9], v[210:213], v[192:195], v[6:9]
	v_mfma_f32_16x16x32_f16 v[2:5], v[222:225], v[192:195], v[2:5]
	s_add_i32 s22, s22, 2
	s_add_u32 s24, s24, 0x100
	s_addc_u32 s25, s25, 0
	s_cmpk_gt_u32 s22, 0x55
	s_mov_b64 s[12:13], s[10:11]
	s_barrier
	s_cbranch_scc0 .LBB0_672
	s_lshl_b32 s10, s92, 8
	s_or_b32 s12, s10, s82
	v_add_u32_e32 v130, s12, v204
	v_ashrrev_i32_e32 v131, 31, v130
	v_lshlrev_b64 v[132:133], 2, v[130:131]
	v_lshl_add_u64 v[134:135], s[38:39], 0, v[132:133]
	v_lshl_add_u64 v[132:133], s[48:49], 0, v[132:133]
	global_load_dword v146, v[134:135], off
	global_load_dword v147, v[132:133], off
	v_readlane_b32 s22, v254, 55
	v_readlane_b32 s23, v254, 56
	s_andn2_b64 vcc, exec, s[22:23]
	v_mov_b32_e32 v148, 0
	v_cndmask_b32_e64 v132, 0, 1, s[22:23]
	v_cmp_ne_u32_e64 s[10:11], 1, v132
	s_cbranch_vccnz .LBB0_675
	v_lshl_add_u64 v[130:131], v[130:131], 2, s[50:51]
	global_load_dword v148, v[130:131], off
